# A/B per sec 6.3: all per-phase s_setprio 1/0 flips deleted from the 5 GEMM K-loops (80 issue slots per 8 phases gone)
# speedup vs baseline: 1.0122x; 1.0122x over previous
; #define PG8_STAGE(bufoff, gbase, v0, v1) do { \
;         __builtin_amdgcn_global_load_lds((const unsigned*)((const char*)(gbase) + (v0)), (LAS unsigned*)(lds + (bufoff) + ldsw), 16, 0, 0); \
;         __builtin_amdgcn_global_load_lds((const unsigned*)((const char*)(gbase) + (v1)), (LAS unsigned*)(lds + (bufoff) + ldsw + 8192), 16, 0, 0); } while (0)
; #define PG8_LDA(dst, b, h) do { _Pragma("unroll") for (int m = 0; m < 4; ++m) _Pragma("unroll") for (int k = 0; k < 2; ++k) dst[m][k] = *(const LAS bf16x8*)(lds + PG8_SA(b, h) + aoff + m * 2048 + k * 1024); } while (0)
; #define PG8_LDB(dst, b, h) do { _Pragma("unroll") for (int n = 0; n < 2; ++n) _Pragma("unroll") for (int k = 0; k < 2; ++k) dst[n][k] = *(const LAS bf16x8*)(lds + PG8_SB(b, h) + boff + n * 2048 + k * 1024); } while (0)
; #define PG8_MMA(ai, bj, At, Bt) do { __builtin_amdgcn_s_setprio(1); _Pragma("unroll") for (int m = 0; m < 4; ++m) _Pragma("unroll") for (int n = 0; n < 2; ++n) _Pragma("unroll") for (int k = 0; k < 2; ++k) \
;         acc[ai][bj][m][n] = __builtin_amdgcn_mfma_f32_16x16x32_bf16(Bt[n][k], At[m][k], acc[ai][bj][m][n], 0, 0, 0); __builtin_amdgcn_s_setprio(0); } while (0)
; template <class Epi, class Sched>
; __device__ __forceinline__ void gemm_phase(LAS unsigned char* lds, const Sched& S, const Epi& E) {
;     ...
;         for (int t = 0; t < nt; t += 2) {
;             const bool last = (t == nt - 2);
;             const char* a1 = cA + (size_t)(t + 1) * kstep;
;             const char* a2 = last ? nA : cA + (size_t)(t + 2) * kstep; const char* b2 = last ? nB : cB + (size_t)(t + 2) * kstep;
;             const char* a3 = a2 + kstep; const char* b3 = b2 + kstep;
;             const unsigned xA0 = last ? nvA0 : vA0, xA1 = last ? nvA1 : vA1, xB0 = last ? nvB0 : vB0, xB1 = last ? nvB1 : vB1;
;             const size_t xhA = last ? nhA : hA, xhB = last ? nhB : hB;
;             PG8_LDB(B0, 0, 0); PG8_SCHED; PG8_LDA(At, 0, 0); PG8_STAGE(PG8_SA(1, 1), a1 + hA, vA0, vA1);
;             PG8_WAIT_L(8); PG8_BAR; PG8_WAIT_L(0); PG8_MMA(0, 0, At, B0); PG8_BAR; PG8_SCHED;
;             PG8_LDB(B1, 0, 1); PG8_STAGE(PG8_SB(0, 0), b2, xB0, xB1);
;             PG8_BAR; PG8_WAIT_L(0); PG8_MMA(0, 1, At, B1); PG8_BAR;
;             PG8_LDA(At, 0, 1); PG8_STAGE(PG8_SA(0, 0), a2, xA0, xA1);
;             PG8_BAR; PG8_WAIT_L(0); PG8_MMA(1, 0, At, B0); PG8_BAR; PG8_SCHED;
.LBB0_306:
	s_add_u32 s21, s26, 0xfff80080
	s_addc_u32 s69, s27, -1
	s_and_b64 s[40:41], exec, s[40:41]
	s_cselect_b32 s41, s23, s69
	s_cselect_b32 s40, s22, s21
	s_add_i32 s21, 0, 0x10000
	v_add_u32_e32 v138, s21, v153
	ds_read_b128 v[158:161], v138
	ds_read_b128 v[182:185], v138 offset:1024
	ds_read_b128 v[186:189], v138 offset:2048
	ds_read_b128 v[190:193], v138 offset:3072
	v_lshl_add_u64 v[226:227], s[26:27], 0, v[132:133]
	s_add_i32 m0, s48, 0xc000
	ds_read_b128 v[194:197], v154
	ds_read_b128 v[198:201], v154 offset:1024
	ds_read_b128 v[202:205], v154 offset:2048
	ds_read_b128 v[206:209], v154 offset:3072
	ds_read_b128 v[210:213], v154 offset:4096
	ds_read_b128 v[214:217], v154 offset:5120
	ds_read_b128 v[218:221], v154 offset:6144
	ds_read_b128 v[222:225], v154 offset:7168
	global_load_lds_dwordx4 v[226:227], off
	v_lshl_add_u64 v[226:227], s[26:27], 0, v[134:135]
	s_add_i32 m0, s48, 0xe000
	s_nop 0
	global_load_lds_dwordx4 v[226:227], off
	s_waitcnt lgkmcnt(8)
	s_barrier
	s_waitcnt lgkmcnt(0)
	v_mfma_f32_16x16x32_bf16 v[124:127], v[158:161], v[194:197], v[124:127]
	v_mfma_f32_16x16x32_bf16 v[120:123], v[186:189], v[194:197], v[120:123]
	v_mfma_f32_16x16x32_bf16 v[116:119], v[158:161], v[202:205], v[116:119]
	v_mfma_f32_16x16x32_bf16 v[112:115], v[186:189], v[202:205], v[112:115]
	v_mfma_f32_16x16x32_bf16 v[100:103], v[158:161], v[210:213], v[100:103]
	v_mfma_f32_16x16x32_bf16 v[96:99], v[186:189], v[210:213], v[96:99]
	v_mfma_f32_16x16x32_bf16 v[84:87], v[158:161], v[218:221], v[84:87]
	v_mfma_f32_16x16x32_bf16 v[80:83], v[186:189], v[218:221], v[80:83]
	v_mfma_f32_16x16x32_bf16 v[124:127], v[182:185], v[198:201], v[124:127]
	v_mfma_f32_16x16x32_bf16 v[120:123], v[190:193], v[198:201], v[120:123]
	v_mfma_f32_16x16x32_bf16 v[116:119], v[182:185], v[206:209], v[116:119]
	v_mfma_f32_16x16x32_bf16 v[112:115], v[190:193], v[206:209], v[112:115]
	v_mfma_f32_16x16x32_bf16 v[100:103], v[182:185], v[214:217], v[100:103]
	v_mfma_f32_16x16x32_bf16 v[96:99], v[190:193], v[214:217], v[96:99]
	v_mfma_f32_16x16x32_bf16 v[84:87], v[182:185], v[222:225], v[84:87]
	v_mfma_f32_16x16x32_bf16 v[80:83], v[190:193], v[222:225], v[80:83]
	s_barrier
	s_add_i32 s69, 0, 0x14000
	s_add_i32 s21, s21, s43
	v_add_u32_e32 v138, s69, v153
	s_mov_b32 m0, s21
	ds_read_b128 v[226:229], v138
	ds_read_b128 v[230:233], v138 offset:1024
	ds_read_b128 v[234:237], v138 offset:2048
	ds_read_b128 v[238:241], v138 offset:3072
	global_load_lds_dwordx4 v136, s[38:39]
	s_add_i32 m0, s21, 0x2000
	v_mov_b32_e32 v147, v137
	global_load_lds_dwordx4 v146, s[38:39]
	s_barrier
	s_waitcnt lgkmcnt(0)
	v_lshl_add_u64 v[242:243], s[38:39], 0, v[136:137]
	v_lshl_add_u64 v[244:245], s[38:39], 0, v[146:147]
	v_mfma_f32_16x16x32_bf16 v[108:111], v[226:229], v[194:197], v[108:111]
	v_mfma_f32_16x16x32_bf16 v[104:107], v[234:237], v[194:197], v[104:107]
	v_mfma_f32_16x16x32_bf16 v[92:95], v[226:229], v[202:205], v[92:95]
	v_mfma_f32_16x16x32_bf16 v[88:91], v[234:237], v[202:205], v[88:91]
	v_mfma_f32_16x16x32_bf16 v[76:79], v[226:229], v[210:213], v[76:79]
	v_mfma_f32_16x16x32_bf16 v[72:75], v[234:237], v[210:213], v[72:75]
	v_mfma_f32_16x16x32_bf16 v[68:71], v[226:229], v[218:221], v[68:71]
	v_mfma_f32_16x16x32_bf16 v[64:67], v[234:237], v[218:221], v[64:67]
	v_mfma_f32_16x16x32_bf16 v[108:111], v[230:233], v[198:201], v[108:111]
	v_mfma_f32_16x16x32_bf16 v[104:107], v[238:241], v[198:201], v[104:107]
	v_mfma_f32_16x16x32_bf16 v[92:95], v[230:233], v[206:209], v[92:95]
	v_mfma_f32_16x16x32_bf16 v[88:91], v[238:241], v[206:209], v[88:91]
	v_mfma_f32_16x16x32_bf16 v[76:79], v[230:233], v[214:217], v[76:79]
	v_mfma_f32_16x16x32_bf16 v[72:75], v[238:241], v[214:217], v[72:75]
	v_mfma_f32_16x16x32_bf16 v[68:71], v[230:233], v[222:225], v[68:71]
	v_mfma_f32_16x16x32_bf16 v[64:67], v[238:241], v[222:225], v[64:67]
	s_mov_b32 m0, s48
	v_lshl_add_u64 v[246:247], s[40:41], 0, v[150:151]
	s_barrier
	ds_read_b128 v[194:197], v154 offset:16384
	ds_read_b128 v[198:201], v154 offset:17408
	ds_read_b128 v[202:205], v154 offset:18432
	ds_read_b128 v[206:209], v154 offset:19456
	ds_read_b128 v[210:213], v154 offset:20480
	ds_read_b128 v[214:217], v154 offset:21504
	ds_read_b128 v[218:221], v154 offset:22528
	ds_read_b128 v[222:225], v154 offset:23552
	global_load_lds_dwordx4 v[246:247], off
	v_lshl_add_u64 v[248:249], s[40:41], 0, v[148:149]
	s_mov_b32 m0, s49
	s_nop 0
	global_load_lds_dwordx4 v[248:249], off
	s_barrier
	s_waitcnt lgkmcnt(0)
	v_mfma_f32_16x16x32_bf16 v[60:63], v[158:161], v[194:197], v[60:63]
	v_mfma_f32_16x16x32_bf16 v[56:59], v[186:189], v[194:197], v[56:59]
	v_mfma_f32_16x16x32_bf16 v[52:55], v[158:161], v[202:205], v[52:55]
	v_mfma_f32_16x16x32_bf16 v[44:47], v[186:189], v[202:205], v[44:47]
	v_mfma_f32_16x16x32_bf16 v[36:39], v[158:161], v[210:213], v[36:39]
	v_mfma_f32_16x16x32_bf16 v[28:31], v[186:189], v[210:213], v[28:31]
	v_mfma_f32_16x16x32_bf16 v[20:23], v[158:161], v[218:221], v[20:23]
	v_mfma_f32_16x16x32_bf16 v[12:15], v[186:189], v[218:221], v[12:15]
	v_mfma_f32_16x16x32_bf16 v[60:63], v[182:185], v[198:201], v[60:63]
	v_mfma_f32_16x16x32_bf16 v[56:59], v[190:193], v[198:201], v[56:59]
	v_mfma_f32_16x16x32_bf16 v[52:55], v[182:185], v[206:209], v[52:55]
	v_mfma_f32_16x16x32_bf16 v[44:47], v[190:193], v[206:209], v[44:47]
	v_mfma_f32_16x16x32_bf16 v[36:39], v[182:185], v[214:217], v[36:39]
	v_mfma_f32_16x16x32_bf16 v[28:31], v[190:193], v[214:217], v[28:31]
	v_mfma_f32_16x16x32_bf16 v[20:23], v[182:185], v[222:225], v[20:23]
	v_mfma_f32_16x16x32_bf16 v[12:15], v[190:193], v[222:225], v[12:15]
	s_barrier
; #define PG8_STAGE(bufoff, gbase, v0, v1) do { \
;         __builtin_amdgcn_global_load_lds((const unsigned*)((const char*)(gbase) + (v0)), (LAS unsigned*)(lds + (bufoff) + ldsw), 16, 0, 0); \
;         __builtin_amdgcn_global_load_lds((const unsigned*)((const char*)(gbase) + (v1)), (LAS unsigned*)(lds + (bufoff) + ldsw + 8192), 16, 0, 0); } while (0)
; #define PG8_LDA(dst, b, h) do { _Pragma("unroll") for (int m = 0; m < 4; ++m) _Pragma("unroll") for (int k = 0; k < 2; ++k) dst[m][k] = *(const LAS bf16x8*)(lds + PG8_SA(b, h) + aoff + m * 2048 + k * 1024); } while (0)
; #define PG8_LDB(dst, b, h) do { _Pragma("unroll") for (int n = 0; n < 2; ++n) _Pragma("unroll") for (int k = 0; k < 2; ++k) dst[n][k] = *(const LAS bf16x8*)(lds + PG8_SB(b, h) + boff + n * 2048 + k * 1024); } while (0)
; #define PG8_MMA(ai, bj, At, Bt) do { __builtin_amdgcn_s_setprio(1); _Pragma("unroll") for (int m = 0; m < 4; ++m) _Pragma("unroll") for (int n = 0; n < 2; ++n) _Pragma("unroll") for (int k = 0; k < 2; ++k) \
;         acc[ai][bj][m][n] = __builtin_amdgcn_mfma_f32_16x16x32_bf16(Bt[n][k], At[m][k], acc[ai][bj][m][n], 0, 0, 0); __builtin_amdgcn_s_setprio(0); } while (0)
; #define PG8_WAIT_V(n) asm volatile("s_waitcnt vmcnt(" #n ")" ::: "memory")
; #define PG8_WAIT_L(n) asm volatile("s_waitcnt lgkmcnt(" #n ")" ::: "memory")
; #define PG8_BAR __builtin_amdgcn_s_barrier()
; #define PG8_SCHED __builtin_amdgcn_sched_barrier(0)
; template <class Epi, class Sched>
; __device__ __forceinline__ void gemm_phase(LAS unsigned char* lds, const Sched& S, const Epi& E) {
;     ...
;             PG8_STAGE(PG8_SB(0, 1), b2 + xhB, xB0, xB1);
;             PG8_WAIT_V(6); PG8_BAR; PG8_MMA(1, 1, At, B1); PG8_BAR;
;             PG8_LDB(B0, 1, 0); PG8_SCHED; PG8_LDA(At, 1, 0); PG8_STAGE(PG8_SA(0, 1), a2 + xhA, xA0, xA1);
;             PG8_WAIT_L(8); PG8_BAR; PG8_WAIT_L(0); PG8_MMA(0, 0, At, B0); PG8_BAR; PG8_SCHED;
;             PG8_LDB(B1, 1, 1); PG8_STAGE(PG8_SB(1, 0), b3, xB0, xB1);
;             PG8_BAR; PG8_WAIT_L(0); PG8_MMA(0, 1, At, B1); PG8_BAR;
	s_add_u32 s70, s38, 0x80000
	s_addc_u32 s71, s39, 0
	s_add_i32 s21, s69, s43
	s_mov_b32 m0, s21
	s_nop 0
	global_load_lds_dwordx4 v136, s[70:71]
	s_add_i32 m0, s21, 0x2000
	s_nop 0
	global_load_lds_dwordx4 v146, s[70:71]
	s_waitcnt vmcnt(6)
	s_barrier
	v_mfma_f32_16x16x32_bf16 v[48:51], v[226:229], v[194:197], v[48:51]
	v_mfma_f32_16x16x32_bf16 v[40:43], v[234:237], v[194:197], v[40:43]
	v_mfma_f32_16x16x32_bf16 v[32:35], v[226:229], v[202:205], v[32:35]
	v_mfma_f32_16x16x32_bf16 v[24:27], v[234:237], v[202:205], v[24:27]
	v_mfma_f32_16x16x32_bf16 v[16:19], v[226:229], v[210:213], v[16:19]
	v_mfma_f32_16x16x32_bf16 v[8:11], v[234:237], v[210:213], v[8:11]
	v_mfma_f32_16x16x32_bf16 v[4:7], v[226:229], v[218:221], v[4:7]
	v_mfma_f32_16x16x32_bf16 v[0:3], v[234:237], v[218:221], v[0:3]
	v_mfma_f32_16x16x32_bf16 v[48:51], v[230:233], v[198:201], v[48:51]
	v_mfma_f32_16x16x32_bf16 v[40:43], v[238:241], v[198:201], v[40:43]
	v_mfma_f32_16x16x32_bf16 v[32:35], v[230:233], v[206:209], v[32:35]
	v_mfma_f32_16x16x32_bf16 v[24:27], v[238:241], v[206:209], v[24:27]
	v_mfma_f32_16x16x32_bf16 v[16:19], v[230:233], v[214:217], v[16:19]
	v_mfma_f32_16x16x32_bf16 v[8:11], v[238:241], v[214:217], v[8:11]
	v_mfma_f32_16x16x32_bf16 v[4:7], v[230:233], v[222:225], v[4:7]
	v_mfma_f32_16x16x32_bf16 v[0:3], v[238:241], v[222:225], v[0:3]
	s_add_i32 s21, 0, 0x18000
	v_add_u32_e32 v138, s21, v153
	s_barrier
	ds_read_b128 v[158:161], v138
	ds_read_b128 v[182:185], v138 offset:1024
	ds_read_b128 v[186:189], v138 offset:2048
	ds_read_b128 v[190:193], v138 offset:3072
	s_add_u32 s40, s40, 0x80000
	s_addc_u32 s41, s41, 0
	s_mov_b32 m0, s50
	v_lshl_add_u64 v[150:151], s[40:41], 0, v[150:151]
	ds_read_b128 v[194:197], v154 offset:32768
	ds_read_b128 v[198:201], v154 offset:33792
	ds_read_b128 v[202:205], v154 offset:34816
	ds_read_b128 v[206:209], v154 offset:35840
	ds_read_b128 v[210:213], v154 offset:36864
	ds_read_b128 v[214:217], v154 offset:37888
	ds_read_b128 v[218:221], v154 offset:38912
	ds_read_b128 v[222:225], v154 offset:39936
	global_load_lds_dwordx4 v[150:151], off
	v_lshl_add_u64 v[148:149], s[40:41], 0, v[148:149]
	s_mov_b32 m0, s51
	s_nop 0
	global_load_lds_dwordx4 v[148:149], off
	s_waitcnt lgkmcnt(8)
	s_barrier
	s_waitcnt lgkmcnt(0)
	v_mfma_f32_16x16x32_bf16 v[124:127], v[158:161], v[194:197], v[124:127]
	v_mfma_f32_16x16x32_bf16 v[120:123], v[186:189], v[194:197], v[120:123]
	v_mfma_f32_16x16x32_bf16 v[116:119], v[158:161], v[202:205], v[116:119]
	v_mfma_f32_16x16x32_bf16 v[112:115], v[186:189], v[202:205], v[112:115]
	v_mfma_f32_16x16x32_bf16 v[100:103], v[158:161], v[210:213], v[100:103]
	v_mfma_f32_16x16x32_bf16 v[96:99], v[186:189], v[210:213], v[96:99]
	v_mfma_f32_16x16x32_bf16 v[84:87], v[158:161], v[218:221], v[84:87]
	v_mfma_f32_16x16x32_bf16 v[80:83], v[186:189], v[218:221], v[80:83]
	v_mfma_f32_16x16x32_bf16 v[124:127], v[182:185], v[198:201], v[124:127]
	v_mfma_f32_16x16x32_bf16 v[120:123], v[190:193], v[198:201], v[120:123]
	v_mfma_f32_16x16x32_bf16 v[116:119], v[182:185], v[206:209], v[116:119]
	v_mfma_f32_16x16x32_bf16 v[112:115], v[190:193], v[206:209], v[112:115]
	v_mfma_f32_16x16x32_bf16 v[100:103], v[182:185], v[214:217], v[100:103]
	v_mfma_f32_16x16x32_bf16 v[96:99], v[190:193], v[214:217], v[96:99]
	v_mfma_f32_16x16x32_bf16 v[84:87], v[182:185], v[222:225], v[84:87]
	v_mfma_f32_16x16x32_bf16 v[80:83], v[190:193], v[222:225], v[80:83]
	s_barrier
	s_add_i32 s40, 0, 0x1c000
	s_add_i32 s21, s21, s43
	v_add_u32_e32 v138, s40, v153
	v_lshl_add_u64 v[238:239], v[242:243], 0, s[44:45]
	s_mov_b32 m0, s21
	ds_read_b128 v[148:151], v138
	ds_read_b128 v[226:229], v138 offset:1024
	ds_read_b128 v[230:233], v138 offset:2048
	ds_read_b128 v[234:237], v138 offset:3072
	global_load_lds_dwordx4 v[238:239], off
	v_lshl_add_u64 v[238:239], v[244:245], 0, s[44:45]
	s_add_i32 m0, s21, 0x2000
	s_nop 0
	global_load_lds_dwordx4 v[238:239], off
	s_barrier
; #define PG8_STAGE(bufoff, gbase, v0, v1) do { \
;         __builtin_amdgcn_global_load_lds((const unsigned*)((const char*)(gbase) + (v0)), (LAS unsigned*)(lds + (bufoff) + ldsw), 16, 0, 0); \
;         __builtin_amdgcn_global_load_lds((const unsigned*)((const char*)(gbase) + (v1)), (LAS unsigned*)(lds + (bufoff) + ldsw + 8192), 16, 0, 0); } while (0)
; #define PG8_LDA(dst, b, h) do { _Pragma("unroll") for (int m = 0; m < 4; ++m) _Pragma("unroll") for (int k = 0; k < 2; ++k) dst[m][k] = *(const LAS bf16x8*)(lds + PG8_SA(b, h) + aoff + m * 2048 + k * 1024); } while (0)
; #define PG8_MMA(ai, bj, At, Bt) do { __builtin_amdgcn_s_setprio(1); _Pragma("unroll") for (int m = 0; m < 4; ++m) _Pragma("unroll") for (int n = 0; n < 2; ++n) _Pragma("unroll") for (int k = 0; k < 2; ++k) \
;         acc[ai][bj][m][n] = __builtin_amdgcn_mfma_f32_16x16x32_bf16(Bt[n][k], At[m][k], acc[ai][bj][m][n], 0, 0, 0); __builtin_amdgcn_s_setprio(0); } while (0)
; #define PG8_WAIT_V(n) asm volatile("s_waitcnt vmcnt(" #n ")" ::: "memory")
; #define PG8_WAIT_L(n) asm volatile("s_waitcnt lgkmcnt(" #n ")" ::: "memory")
; #define PG8_BAR __builtin_amdgcn_s_barrier()
; #define PG8_SCHED __builtin_amdgcn_sched_barrier(0)
; template <class Epi, class Sched>
; __device__ __forceinline__ void gemm_phase(LAS unsigned char* lds, const Sched& S, const Epi& E) {
;     ...
;             const bool last = (t == nt - 2);
;             const char* a1 = cA + (size_t)(t + 1) * kstep;
;             const char* a2 = last ? nA : cA + (size_t)(t + 2) * kstep; const char* b2 = last ? nB : cB + (size_t)(t + 2) * kstep;
;             const char* a3 = a2 + kstep; const char* b3 = b2 + kstep;
;             const unsigned xA0 = last ? nvA0 : vA0, xA1 = last ? nvA1 : vA1, xB0 = last ? nvB0 : vB0, xB1 = last ? nvB1 : vB1;
;             const size_t xhA = last ? nhA : hA, xhB = last ? nhB : hB;
;     ...
;             PG8_BAR; PG8_WAIT_L(0); PG8_MMA(0, 1, At, B1); PG8_BAR;
;             PG8_LDA(At, 1, 1); PG8_STAGE(PG8_SA(1, 0), a3, xA0, xA1);
;             PG8_BAR; PG8_WAIT_L(0); PG8_MMA(1, 0, At, B0); PG8_BAR; PG8_SCHED;
;             PG8_STAGE(PG8_SB(1, 1), b3 + xhB, xB0, xB1);
;             PG8_WAIT_V(6); PG8_BAR; PG8_MMA(1, 1, At, B1); PG8_BAR;
;         }
	s_waitcnt lgkmcnt(0)
	v_mfma_f32_16x16x32_bf16 v[108:111], v[148:151], v[194:197], v[108:111]
	v_mfma_f32_16x16x32_bf16 v[104:107], v[230:233], v[194:197], v[104:107]
	v_mfma_f32_16x16x32_bf16 v[92:95], v[148:151], v[202:205], v[92:95]
	v_mfma_f32_16x16x32_bf16 v[88:91], v[230:233], v[202:205], v[88:91]
	v_mfma_f32_16x16x32_bf16 v[76:79], v[148:151], v[210:213], v[76:79]
	v_mfma_f32_16x16x32_bf16 v[72:75], v[230:233], v[210:213], v[72:75]
	v_mfma_f32_16x16x32_bf16 v[68:71], v[148:151], v[218:221], v[68:71]
	v_mfma_f32_16x16x32_bf16 v[64:67], v[230:233], v[218:221], v[64:67]
	v_mfma_f32_16x16x32_bf16 v[108:111], v[226:229], v[198:201], v[108:111]
	v_mfma_f32_16x16x32_bf16 v[104:107], v[234:237], v[198:201], v[104:107]
	v_mfma_f32_16x16x32_bf16 v[92:95], v[226:229], v[206:209], v[92:95]
	v_mfma_f32_16x16x32_bf16 v[88:91], v[234:237], v[206:209], v[88:91]
	v_mfma_f32_16x16x32_bf16 v[76:79], v[226:229], v[214:217], v[76:79]
	v_mfma_f32_16x16x32_bf16 v[72:75], v[234:237], v[214:217], v[72:75]
	v_mfma_f32_16x16x32_bf16 v[68:71], v[226:229], v[222:225], v[68:71]
	v_mfma_f32_16x16x32_bf16 v[64:67], v[234:237], v[222:225], v[64:67]
	s_mov_b32 m0, s64
	v_lshl_add_u64 v[238:239], v[246:247], 0, s[44:45]
	s_barrier
	ds_read_b128 v[194:197], v154 offset:49152
	ds_read_b128 v[198:201], v154 offset:50176
	ds_read_b128 v[202:205], v154 offset:51200
	ds_read_b128 v[206:209], v154 offset:52224
	ds_read_b128 v[210:213], v154 offset:53248
	ds_read_b128 v[214:217], v154 offset:54272
	ds_read_b128 v[218:221], v154 offset:55296
	ds_read_b128 v[222:225], v154 offset:56320
	global_load_lds_dwordx4 v[238:239], off
	v_lshl_add_u64 v[238:239], v[248:249], 0, s[44:45]
	s_mov_b32 m0, s65
	s_nop 0
	global_load_lds_dwordx4 v[238:239], off
	s_barrier
	s_waitcnt lgkmcnt(0)
	v_mfma_f32_16x16x32_bf16 v[60:63], v[158:161], v[194:197], v[60:63]
	v_mfma_f32_16x16x32_bf16 v[56:59], v[186:189], v[194:197], v[56:59]
	v_mfma_f32_16x16x32_bf16 v[52:55], v[158:161], v[202:205], v[52:55]
	v_mfma_f32_16x16x32_bf16 v[44:47], v[186:189], v[202:205], v[44:47]
	v_mfma_f32_16x16x32_bf16 v[36:39], v[158:161], v[210:213], v[36:39]
	v_mfma_f32_16x16x32_bf16 v[28:31], v[186:189], v[210:213], v[28:31]
	v_mfma_f32_16x16x32_bf16 v[20:23], v[158:161], v[218:221], v[20:23]
	v_mfma_f32_16x16x32_bf16 v[12:15], v[186:189], v[218:221], v[12:15]
	v_mfma_f32_16x16x32_bf16 v[60:63], v[182:185], v[198:201], v[60:63]
	v_mfma_f32_16x16x32_bf16 v[56:59], v[190:193], v[198:201], v[56:59]
	v_mfma_f32_16x16x32_bf16 v[52:55], v[182:185], v[206:209], v[52:55]
	v_mfma_f32_16x16x32_bf16 v[44:47], v[190:193], v[206:209], v[44:47]
	v_mfma_f32_16x16x32_bf16 v[36:39], v[182:185], v[214:217], v[36:39]
	v_mfma_f32_16x16x32_bf16 v[28:31], v[190:193], v[214:217], v[28:31]
	v_mfma_f32_16x16x32_bf16 v[20:23], v[182:185], v[222:225], v[20:23]
	v_mfma_f32_16x16x32_bf16 v[12:15], v[190:193], v[222:225], v[12:15]
	s_barrier
	s_add_u32 s38, s38, 0x80080
	s_addc_u32 s39, s39, 0
	s_add_i32 s21, s40, s43
	s_mov_b32 m0, s21
	s_nop 0
	global_load_lds_dwordx4 v136, s[38:39]
	s_add_i32 m0, s21, 0x2000
	s_nop 0
	global_load_lds_dwordx4 v146, s[38:39]
	s_waitcnt vmcnt(6)
	s_barrier
	v_mfma_f32_16x16x32_bf16 v[48:51], v[148:151], v[194:197], v[48:51]
	v_mfma_f32_16x16x32_bf16 v[40:43], v[230:233], v[194:197], v[40:43]
	v_mfma_f32_16x16x32_bf16 v[32:35], v[148:151], v[202:205], v[32:35]
	v_mfma_f32_16x16x32_bf16 v[24:27], v[230:233], v[202:205], v[24:27]
	v_mfma_f32_16x16x32_bf16 v[16:19], v[148:151], v[210:213], v[16:19]
	v_mfma_f32_16x16x32_bf16 v[8:11], v[230:233], v[210:213], v[8:11]
	v_mfma_f32_16x16x32_bf16 v[4:7], v[148:151], v[218:221], v[4:7]
	v_mfma_f32_16x16x32_bf16 v[0:3], v[230:233], v[218:221], v[0:3]
	v_mfma_f32_16x16x32_bf16 v[48:51], v[226:229], v[198:201], v[48:51]
	v_mfma_f32_16x16x32_bf16 v[40:43], v[234:237], v[198:201], v[40:43]
	v_mfma_f32_16x16x32_bf16 v[32:35], v[226:229], v[206:209], v[32:35]
	v_mfma_f32_16x16x32_bf16 v[24:27], v[234:237], v[206:209], v[24:27]
	v_mfma_f32_16x16x32_bf16 v[16:19], v[226:229], v[214:217], v[16:19]
	v_mfma_f32_16x16x32_bf16 v[8:11], v[234:237], v[214:217], v[8:11]
	v_mfma_f32_16x16x32_bf16 v[4:7], v[226:229], v[222:225], v[4:7]
	v_mfma_f32_16x16x32_bf16 v[0:3], v[234:237], v[222:225], v[0:3]
	s_add_i32 s15, s15, 2
	s_add_u32 s26, s26, 0x100
	s_addc_u32 s27, s27, 0
	s_add_u32 s34, s34, 0x100
	s_addc_u32 s35, s35, 0
	s_cmp_gt_u32 s15, 29
	s_cbranch_scc1 .Lrot_exit_0
	s_cmp_eq_u32 s15, 28
	s_cselect_b64 s[40:41], -1, 0
	s_and_b64 vcc, exec, s[40:41]
	v_mov_b64_e32 v[148:149], v[130:131]
	v_mov_b64_e32 v[150:151], v[128:129]
	v_mov_b32_e32 v146, v156
	v_mov_b32_e32 v136, v155
	s_mov_b64 s[38:39], s[24:25]
	s_cbranch_vccnz .Lrot_join_0
	v_mov_b64_e32 v[148:149], v[134:135]
	v_mov_b64_e32 v[150:151], v[132:133]
	v_mov_b32_e32 v146, v142
	v_mov_b32_e32 v136, v144
	s_mov_b64 s[38:39], s[34:35]

; #define PG8_STAGE(bufoff, gbase, v0, v1) do { \
;         __builtin_amdgcn_global_load_lds((const unsigned*)((const char*)(gbase) + (v0)), (LAS unsigned*)(lds + (bufoff) + ldsw), 16, 0, 0); \
;         __builtin_amdgcn_global_load_lds((const unsigned*)((const char*)(gbase) + (v1)), (LAS unsigned*)(lds + (bufoff) + ldsw + 8192), 16, 0, 0); } while (0)
; #define PG8_LDA(dst, b, h) do { _Pragma("unroll") for (int m = 0; m < 4; ++m) _Pragma("unroll") for (int k = 0; k < 2; ++k) dst[m][k] = *(const LAS bf16x8*)(lds + PG8_SA(b, h) + aoff + m * 2048 + k * 1024); } while (0)
; #define PG8_LDB(dst, b, h) do { _Pragma("unroll") for (int n = 0; n < 2; ++n) _Pragma("unroll") for (int k = 0; k < 2; ++k) dst[n][k] = *(const LAS bf16x8*)(lds + PG8_SB(b, h) + boff + n * 2048 + k * 1024); } while (0)
; #define PG8_MMA(ai, bj, At, Bt) do { __builtin_amdgcn_s_setprio(1); _Pragma("unroll") for (int m = 0; m < 4; ++m) _Pragma("unroll") for (int n = 0; n < 2; ++n) _Pragma("unroll") for (int k = 0; k < 2; ++k) \
;         acc[ai][bj][m][n] = __builtin_amdgcn_mfma_f32_16x16x32_bf16(Bt[n][k], At[m][k], acc[ai][bj][m][n], 0, 0, 0); __builtin_amdgcn_s_setprio(0); } while (0)
; template <class Epi, class Sched>
; __device__ __forceinline__ void gemm_phase(LAS unsigned char* lds, const Sched& S, const Epi& E) {
;     ...
;         for (int t = 0; t < nt; t += 2) {
;             const bool last = (t == nt - 2);
;             const char* a1 = cA + (size_t)(t + 1) * kstep;
;             const char* a2 = last ? nA : cA + (size_t)(t + 2) * kstep; const char* b2 = last ? nB : cB + (size_t)(t + 2) * kstep;
;             const char* a3 = a2 + kstep; const char* b3 = b2 + kstep;
;             const unsigned xA0 = last ? nvA0 : vA0, xA1 = last ? nvA1 : vA1, xB0 = last ? nvB0 : vB0, xB1 = last ? nvB1 : vB1;
;             const size_t xhA = last ? nhA : hA, xhB = last ? nhB : hB;
;             PG8_LDB(B0, 0, 0); PG8_SCHED; PG8_LDA(At, 0, 0); PG8_STAGE(PG8_SA(1, 1), a1 + hA, vA0, vA1);
;             PG8_WAIT_L(8); PG8_BAR; PG8_WAIT_L(0); PG8_MMA(0, 0, At, B0); PG8_BAR; PG8_SCHED;
;             PG8_LDB(B1, 0, 1); PG8_STAGE(PG8_SB(0, 0), b2, xB0, xB1);
;             PG8_BAR; PG8_WAIT_L(0); PG8_MMA(0, 1, At, B1); PG8_BAR;
;             PG8_LDA(At, 0, 1); PG8_STAGE(PG8_SA(0, 0), a2, xA0, xA1);
;             PG8_BAR; PG8_WAIT_L(0); PG8_MMA(1, 0, At, B0); PG8_BAR; PG8_SCHED;
.LBB0_574:
	s_add_i32 s49, s49, 2
	s_add_u32 s65, s34, 0x80
	s_addc_u32 vcc_lo, s35, 0
	s_and_b64 s[54:55], exec, s[54:55]
	s_cselect_b32 s55, s41, vcc_lo
	s_cselect_b32 s54, s40, s65
	s_add_i32 s65, 0, 0x10000
	v_add_u32_e32 v138, s65, v184
	ds_read_b128 v[158:161], v138
	ds_read_b128 v[186:189], v138 offset:1024
	ds_read_b128 v[190:193], v138 offset:2048
	ds_read_b128 v[194:197], v138 offset:3072
	v_lshl_add_u64 v[230:231], s[34:35], 0, v[134:135]
	s_add_i32 m0, s91, 0xc000
	ds_read_b128 v[198:201], v185
	ds_read_b128 v[202:205], v185 offset:1024
	ds_read_b128 v[206:209], v185 offset:2048
	ds_read_b128 v[210:213], v185 offset:3072
	ds_read_b128 v[214:217], v185 offset:4096
	ds_read_b128 v[218:221], v185 offset:5120
	ds_read_b128 v[222:225], v185 offset:6144
	ds_read_b128 v[226:229], v185 offset:7168
	global_load_lds_dwordx4 v[230:231], off
	v_lshl_add_u64 v[230:231], s[34:35], 0, v[150:151]
	s_add_i32 m0, s91, 0xe000
	s_nop 0
	global_load_lds_dwordx4 v[230:231], off
	s_waitcnt lgkmcnt(8)
	s_barrier
	s_waitcnt lgkmcnt(0)
	v_mfma_f32_16x16x32_bf16 v[124:127], v[158:161], v[198:201], v[124:127]
	v_mfma_f32_16x16x32_bf16 v[120:123], v[190:193], v[198:201], v[120:123]
	v_mfma_f32_16x16x32_bf16 v[116:119], v[158:161], v[206:209], v[116:119]
	v_mfma_f32_16x16x32_bf16 v[112:115], v[190:193], v[206:209], v[112:115]
	v_mfma_f32_16x16x32_bf16 v[108:111], v[158:161], v[214:217], v[108:111]
	v_mfma_f32_16x16x32_bf16 v[104:107], v[190:193], v[214:217], v[104:107]
	v_mfma_f32_16x16x32_bf16 v[100:103], v[158:161], v[222:225], v[100:103]
	v_mfma_f32_16x16x32_bf16 v[96:99], v[190:193], v[222:225], v[96:99]
	v_mfma_f32_16x16x32_bf16 v[124:127], v[186:189], v[202:205], v[124:127]
	v_mfma_f32_16x16x32_bf16 v[120:123], v[194:197], v[202:205], v[120:123]
	v_mfma_f32_16x16x32_bf16 v[116:119], v[186:189], v[210:213], v[116:119]
	v_mfma_f32_16x16x32_bf16 v[112:115], v[194:197], v[210:213], v[112:115]
	v_mfma_f32_16x16x32_bf16 v[108:111], v[186:189], v[218:221], v[108:111]
	v_mfma_f32_16x16x32_bf16 v[104:107], v[194:197], v[218:221], v[104:107]
	v_mfma_f32_16x16x32_bf16 v[100:103], v[186:189], v[226:229], v[100:103]
	v_mfma_f32_16x16x32_bf16 v[96:99], v[194:197], v[226:229], v[96:99]
	s_barrier
	s_add_i32 vcc_lo, 0, 0x14000
	s_add_i32 s65, s65, s9
	v_add_u32_e32 v138, vcc_lo, v184
	s_mov_b32 m0, s65
	ds_read_b128 v[230:233], v138
	ds_read_b128 v[234:237], v138 offset:1024
	ds_read_b128 v[238:241], v138 offset:2048
	ds_read_b128 v[242:245], v138 offset:3072
	global_load_lds_dwordx4 v136, s[92:93]
	s_add_i32 m0, s65, 0x2000
	v_mov_b32_e32 v157, v137
	global_load_lds_dwordx4 v156, s[92:93]
	s_barrier
	s_waitcnt lgkmcnt(0)
	v_lshl_add_u64 v[246:247], s[92:93], 0, v[136:137]
	v_lshl_add_u64 v[248:249], s[92:93], 0, v[156:157]
	v_mfma_f32_16x16x32_bf16 v[92:95], v[230:233], v[198:201], v[92:95]
	v_mfma_f32_16x16x32_bf16 v[88:91], v[238:241], v[198:201], v[88:91]
	v_mfma_f32_16x16x32_bf16 v[84:87], v[230:233], v[206:209], v[84:87]
	v_mfma_f32_16x16x32_bf16 v[80:83], v[238:241], v[206:209], v[80:83]
	v_mfma_f32_16x16x32_bf16 v[76:79], v[230:233], v[214:217], v[76:79]
	v_mfma_f32_16x16x32_bf16 v[72:75], v[238:241], v[214:217], v[72:75]
	v_mfma_f32_16x16x32_bf16 v[68:71], v[230:233], v[222:225], v[68:71]
	v_mfma_f32_16x16x32_bf16 v[64:67], v[238:241], v[222:225], v[64:67]
	v_mfma_f32_16x16x32_bf16 v[92:95], v[234:237], v[202:205], v[92:95]
	v_mfma_f32_16x16x32_bf16 v[88:91], v[242:245], v[202:205], v[88:91]
	v_mfma_f32_16x16x32_bf16 v[84:87], v[234:237], v[210:213], v[84:87]
	v_mfma_f32_16x16x32_bf16 v[80:83], v[242:245], v[210:213], v[80:83]
	v_mfma_f32_16x16x32_bf16 v[76:79], v[234:237], v[218:221], v[76:79]
	v_mfma_f32_16x16x32_bf16 v[72:75], v[242:245], v[218:221], v[72:75]
	v_mfma_f32_16x16x32_bf16 v[68:71], v[234:237], v[226:229], v[68:71]
	v_mfma_f32_16x16x32_bf16 v[64:67], v[242:245], v[226:229], v[64:67]
	s_mov_b32 m0, s91
	v_lshl_add_u64 v[250:251], s[54:55], 0, v[154:155]
	s_barrier
	ds_read_b128 v[198:201], v185 offset:16384
	ds_read_b128 v[202:205], v185 offset:17408
	ds_read_b128 v[206:209], v185 offset:18432
	ds_read_b128 v[210:213], v185 offset:19456
	ds_read_b128 v[214:217], v185 offset:20480
	ds_read_b128 v[218:221], v185 offset:21504
	ds_read_b128 v[222:225], v185 offset:22528
	ds_read_b128 v[226:229], v185 offset:23552
	global_load_lds_dwordx4 v[250:251], off
	v_lshl_add_u64 v[140:141], s[54:55], 0, v[152:153]
	s_mov_b32 m0, s50
	s_nop 0
	global_load_lds_dwordx4 v[140:141], off
	s_barrier
	s_waitcnt lgkmcnt(0)
	v_mfma_f32_16x16x32_bf16 v[60:63], v[158:161], v[198:201], v[60:63]
	v_mfma_f32_16x16x32_bf16 v[56:59], v[190:193], v[198:201], v[56:59]
	v_mfma_f32_16x16x32_bf16 v[52:55], v[158:161], v[206:209], v[52:55]
	v_mfma_f32_16x16x32_bf16 v[48:51], v[190:193], v[206:209], v[48:51]
	v_mfma_f32_16x16x32_bf16 v[44:47], v[158:161], v[214:217], v[44:47]
	v_mfma_f32_16x16x32_bf16 v[40:43], v[190:193], v[214:217], v[40:43]
	v_mfma_f32_16x16x32_bf16 v[36:39], v[158:161], v[222:225], v[36:39]
	v_mfma_f32_16x16x32_bf16 v[32:35], v[190:193], v[222:225], v[32:35]
	v_mfma_f32_16x16x32_bf16 v[60:63], v[186:189], v[202:205], v[60:63]
	v_mfma_f32_16x16x32_bf16 v[56:59], v[194:197], v[202:205], v[56:59]
	v_mfma_f32_16x16x32_bf16 v[52:55], v[186:189], v[210:213], v[52:55]
	v_mfma_f32_16x16x32_bf16 v[48:51], v[194:197], v[210:213], v[48:51]
	v_mfma_f32_16x16x32_bf16 v[44:47], v[186:189], v[218:221], v[44:47]
	v_mfma_f32_16x16x32_bf16 v[40:43], v[194:197], v[218:221], v[40:43]
	v_mfma_f32_16x16x32_bf16 v[36:39], v[186:189], v[226:229], v[36:39]
	v_mfma_f32_16x16x32_bf16 v[32:35], v[194:197], v[226:229], v[32:35]
	s_barrier
; #define PG8_STAGE(bufoff, gbase, v0, v1) do { \
;         __builtin_amdgcn_global_load_lds((const unsigned*)((const char*)(gbase) + (v0)), (LAS unsigned*)(lds + (bufoff) + ldsw), 16, 0, 0); \
;         __builtin_amdgcn_global_load_lds((const unsigned*)((const char*)(gbase) + (v1)), (LAS unsigned*)(lds + (bufoff) + ldsw + 8192), 16, 0, 0); } while (0)
; #define PG8_LDA(dst, b, h) do { _Pragma("unroll") for (int m = 0; m < 4; ++m) _Pragma("unroll") for (int k = 0; k < 2; ++k) dst[m][k] = *(const LAS bf16x8*)(lds + PG8_SA(b, h) + aoff + m * 2048 + k * 1024); } while (0)
; #define PG8_LDB(dst, b, h) do { _Pragma("unroll") for (int n = 0; n < 2; ++n) _Pragma("unroll") for (int k = 0; k < 2; ++k) dst[n][k] = *(const LAS bf16x8*)(lds + PG8_SB(b, h) + boff + n * 2048 + k * 1024); } while (0)
; #define PG8_MMA(ai, bj, At, Bt) do { __builtin_amdgcn_s_setprio(1); _Pragma("unroll") for (int m = 0; m < 4; ++m) _Pragma("unroll") for (int n = 0; n < 2; ++n) _Pragma("unroll") for (int k = 0; k < 2; ++k) \
;         acc[ai][bj][m][n] = __builtin_amdgcn_mfma_f32_16x16x32_bf16(Bt[n][k], At[m][k], acc[ai][bj][m][n], 0, 0, 0); __builtin_amdgcn_s_setprio(0); } while (0)
; #define PG8_WAIT_V(n) asm volatile("s_waitcnt vmcnt(" #n ")" ::: "memory")
; #define PG8_WAIT_L(n) asm volatile("s_waitcnt lgkmcnt(" #n ")" ::: "memory")
; #define PG8_BAR __builtin_amdgcn_s_barrier()
; #define PG8_SCHED __builtin_amdgcn_sched_barrier(0)
; template <class Epi, class Sched>
; __device__ __forceinline__ void gemm_phase(LAS unsigned char* lds, const Sched& S, const Epi& E) {
;     ...
;             PG8_STAGE(PG8_SB(0, 1), b2 + xhB, xB0, xB1);
;             PG8_WAIT_V(6); PG8_BAR; PG8_MMA(1, 1, At, B1); PG8_BAR;
;             PG8_LDB(B0, 1, 0); PG8_SCHED; PG8_LDA(At, 1, 0); PG8_STAGE(PG8_SA(0, 1), a2 + xhA, xA0, xA1);
;             PG8_WAIT_L(8); PG8_BAR; PG8_WAIT_L(0); PG8_MMA(0, 0, At, B0); PG8_BAR; PG8_SCHED;
;             PG8_LDB(B1, 1, 1); PG8_STAGE(PG8_SB(1, 0), b3, xB0, xB1);
;             PG8_BAR; PG8_WAIT_L(0); PG8_MMA(0, 1, At, B1); PG8_BAR;
	s_add_u32 s88, s92, s88
	s_addc_u32 s89, s93, s89
	s_add_i32 s65, vcc_lo, s9
	s_mov_b32 m0, s65
	v_lshl_add_u64 v[160:161], s[88:89], 0, v[136:137]
	global_load_lds_dwordx4 v136, s[88:89]
	s_add_i32 m0, s65, 0x2000
	v_lshl_add_u64 v[138:139], s[88:89], 0, v[156:157]
	global_load_lds_dwordx4 v156, s[88:89]
	s_waitcnt vmcnt(6)
	s_barrier
	v_mfma_f32_16x16x32_bf16 v[28:31], v[230:233], v[198:201], v[28:31]
	v_mfma_f32_16x16x32_bf16 v[24:27], v[238:241], v[198:201], v[24:27]
	v_mfma_f32_16x16x32_bf16 v[20:23], v[230:233], v[206:209], v[20:23]
	v_mfma_f32_16x16x32_bf16 v[16:19], v[238:241], v[206:209], v[16:19]
	v_mfma_f32_16x16x32_bf16 v[12:15], v[230:233], v[214:217], v[12:15]
	v_mfma_f32_16x16x32_bf16 v[8:11], v[238:241], v[214:217], v[8:11]
	v_mfma_f32_16x16x32_bf16 v[4:7], v[230:233], v[222:225], v[4:7]
	v_mfma_f32_16x16x32_bf16 v[0:3], v[238:241], v[222:225], v[0:3]
	v_mfma_f32_16x16x32_bf16 v[28:31], v[234:237], v[202:205], v[28:31]
	v_mfma_f32_16x16x32_bf16 v[24:27], v[242:245], v[202:205], v[24:27]
	v_mfma_f32_16x16x32_bf16 v[20:23], v[234:237], v[210:213], v[20:23]
	v_mfma_f32_16x16x32_bf16 v[16:19], v[242:245], v[210:213], v[16:19]
	v_mfma_f32_16x16x32_bf16 v[12:15], v[234:237], v[218:221], v[12:15]
	v_mfma_f32_16x16x32_bf16 v[8:11], v[242:245], v[218:221], v[8:11]
	v_mfma_f32_16x16x32_bf16 v[4:7], v[234:237], v[226:229], v[4:7]
	v_mfma_f32_16x16x32_bf16 v[0:3], v[242:245], v[226:229], v[0:3]
	s_add_i32 s65, 0, 0x18000
	v_add_u32_e32 v136, s65, v184
	s_barrier
	ds_read_b128 v[156:159], v136
	ds_read_b128 v[186:189], v136 offset:1024
	ds_read_b128 v[190:193], v136 offset:2048
	ds_read_b128 v[194:197], v136 offset:3072
	s_add_u32 s54, s54, s82
	s_addc_u32 s55, s55, s83
	s_mov_b32 m0, s51
	v_lshl_add_u64 v[154:155], s[54:55], 0, v[154:155]
	ds_read_b128 v[198:201], v185 offset:32768
	ds_read_b128 v[202:205], v185 offset:33792
	ds_read_b128 v[206:209], v185 offset:34816
	ds_read_b128 v[210:213], v185 offset:35840
	ds_read_b128 v[214:217], v185 offset:36864
	ds_read_b128 v[218:221], v185 offset:37888
	ds_read_b128 v[222:225], v185 offset:38912
	ds_read_b128 v[226:229], v185 offset:39936
	global_load_lds_dwordx4 v[154:155], off
	v_lshl_add_u64 v[152:153], s[54:55], 0, v[152:153]
	s_mov_b32 m0, s8
	s_nop 0
	global_load_lds_dwordx4 v[152:153], off
	s_waitcnt lgkmcnt(8)
	s_barrier
	s_waitcnt lgkmcnt(0)
	v_mfma_f32_16x16x32_bf16 v[124:127], v[156:159], v[198:201], v[124:127]
	v_mfma_f32_16x16x32_bf16 v[120:123], v[190:193], v[198:201], v[120:123]
	v_mfma_f32_16x16x32_bf16 v[116:119], v[156:159], v[206:209], v[116:119]
	v_mfma_f32_16x16x32_bf16 v[112:115], v[190:193], v[206:209], v[112:115]
	v_mfma_f32_16x16x32_bf16 v[108:111], v[156:159], v[214:217], v[108:111]
	v_mfma_f32_16x16x32_bf16 v[104:107], v[190:193], v[214:217], v[104:107]
	v_mfma_f32_16x16x32_bf16 v[100:103], v[156:159], v[222:225], v[100:103]
	v_mfma_f32_16x16x32_bf16 v[96:99], v[190:193], v[222:225], v[96:99]
	v_mfma_f32_16x16x32_bf16 v[124:127], v[186:189], v[202:205], v[124:127]
	v_mfma_f32_16x16x32_bf16 v[120:123], v[194:197], v[202:205], v[120:123]
	v_mfma_f32_16x16x32_bf16 v[116:119], v[186:189], v[210:213], v[116:119]
	v_mfma_f32_16x16x32_bf16 v[112:115], v[194:197], v[210:213], v[112:115]
	v_mfma_f32_16x16x32_bf16 v[108:111], v[186:189], v[218:221], v[108:111]
	v_mfma_f32_16x16x32_bf16 v[104:107], v[194:197], v[218:221], v[104:107]
	v_mfma_f32_16x16x32_bf16 v[100:103], v[186:189], v[226:229], v[100:103]
	v_mfma_f32_16x16x32_bf16 v[96:99], v[194:197], v[226:229], v[96:99]
	s_barrier
	s_add_i32 s54, 0, 0x1c000
	s_add_i32 s55, s65, s9
	v_add_u32_e32 v136, s54, v184
	v_lshl_add_u64 v[242:243], v[246:247], 0, s[44:45]
	s_mov_b32 m0, s55
	ds_read_b128 v[152:155], v136
	ds_read_b128 v[230:233], v136 offset:1024
	ds_read_b128 v[234:237], v136 offset:2048
	ds_read_b128 v[238:241], v136 offset:3072
	global_load_lds_dwordx4 v[242:243], off
	v_lshl_add_u64 v[242:243], v[248:249], 0, s[44:45]
	s_add_i32 m0, s55, 0x2000
	s_nop 0
	global_load_lds_dwordx4 v[242:243], off
	s_barrier
; #define PG8_STAGE(bufoff, gbase, v0, v1) do { \
;         __builtin_amdgcn_global_load_lds((const unsigned*)((const char*)(gbase) + (v0)), (LAS unsigned*)(lds + (bufoff) + ldsw), 16, 0, 0); \
;         __builtin_amdgcn_global_load_lds((const unsigned*)((const char*)(gbase) + (v1)), (LAS unsigned*)(lds + (bufoff) + ldsw + 8192), 16, 0, 0); } while (0)
; #define PG8_LDA(dst, b, h) do { _Pragma("unroll") for (int m = 0; m < 4; ++m) _Pragma("unroll") for (int k = 0; k < 2; ++k) dst[m][k] = *(const LAS bf16x8*)(lds + PG8_SA(b, h) + aoff + m * 2048 + k * 1024); } while (0)
; #define PG8_MMA(ai, bj, At, Bt) do { __builtin_amdgcn_s_setprio(1); _Pragma("unroll") for (int m = 0; m < 4; ++m) _Pragma("unroll") for (int n = 0; n < 2; ++n) _Pragma("unroll") for (int k = 0; k < 2; ++k) \
;         acc[ai][bj][m][n] = __builtin_amdgcn_mfma_f32_16x16x32_bf16(Bt[n][k], At[m][k], acc[ai][bj][m][n], 0, 0, 0); __builtin_amdgcn_s_setprio(0); } while (0)
; #define PG8_WAIT_V(n) asm volatile("s_waitcnt vmcnt(" #n ")" ::: "memory")
; #define PG8_WAIT_L(n) asm volatile("s_waitcnt lgkmcnt(" #n ")" ::: "memory")
; #define PG8_BAR __builtin_amdgcn_s_barrier()
; #define PG8_SCHED __builtin_amdgcn_sched_barrier(0)
; template <class Epi, class Sched>
; __device__ __forceinline__ void gemm_phase(LAS unsigned char* lds, const Sched& S, const Epi& E) {
;     ...
;             const bool last = (t == nt - 2);
;             const char* a1 = cA + (size_t)(t + 1) * kstep;
;             const char* a2 = last ? nA : cA + (size_t)(t + 2) * kstep; const char* b2 = last ? nB : cB + (size_t)(t + 2) * kstep;
;             const char* a3 = a2 + kstep; const char* b3 = b2 + kstep;
;             const unsigned xA0 = last ? nvA0 : vA0, xA1 = last ? nvA1 : vA1, xB0 = last ? nvB0 : vB0, xB1 = last ? nvB1 : vB1;
;             const size_t xhA = last ? nhA : hA, xhB = last ? nhB : hB;
;     ...
;             PG8_BAR; PG8_WAIT_L(0); PG8_MMA(0, 1, At, B1); PG8_BAR;
;             PG8_LDA(At, 1, 1); PG8_STAGE(PG8_SA(1, 0), a3, xA0, xA1);
;             PG8_BAR; PG8_WAIT_L(0); PG8_MMA(1, 0, At, B0); PG8_BAR; PG8_SCHED;
;             PG8_STAGE(PG8_SB(1, 1), b3 + xhB, xB0, xB1);
;             PG8_WAIT_V(6); PG8_BAR; PG8_MMA(1, 1, At, B1); PG8_BAR;
;         }
	s_waitcnt lgkmcnt(0)
	v_mfma_f32_16x16x32_bf16 v[92:95], v[152:155], v[198:201], v[92:95]
	v_mfma_f32_16x16x32_bf16 v[88:91], v[234:237], v[198:201], v[88:91]
	v_mfma_f32_16x16x32_bf16 v[84:87], v[152:155], v[206:209], v[84:87]
	v_mfma_f32_16x16x32_bf16 v[80:83], v[234:237], v[206:209], v[80:83]
	v_mfma_f32_16x16x32_bf16 v[76:79], v[152:155], v[214:217], v[76:79]
	v_mfma_f32_16x16x32_bf16 v[72:75], v[234:237], v[214:217], v[72:75]
	v_mfma_f32_16x16x32_bf16 v[68:71], v[152:155], v[222:225], v[68:71]
	v_mfma_f32_16x16x32_bf16 v[64:67], v[234:237], v[222:225], v[64:67]
	v_mfma_f32_16x16x32_bf16 v[92:95], v[230:233], v[202:205], v[92:95]
	v_mfma_f32_16x16x32_bf16 v[88:91], v[238:241], v[202:205], v[88:91]
	v_mfma_f32_16x16x32_bf16 v[84:87], v[230:233], v[210:213], v[84:87]
	v_mfma_f32_16x16x32_bf16 v[80:83], v[238:241], v[210:213], v[80:83]
	v_mfma_f32_16x16x32_bf16 v[76:79], v[230:233], v[218:221], v[76:79]
	v_mfma_f32_16x16x32_bf16 v[72:75], v[238:241], v[218:221], v[72:75]
	v_mfma_f32_16x16x32_bf16 v[68:71], v[230:233], v[226:229], v[68:71]
	v_mfma_f32_16x16x32_bf16 v[64:67], v[238:241], v[226:229], v[64:67]
	s_mov_b32 m0, s21
	v_lshl_add_u64 v[242:243], v[250:251], 0, s[44:45]
	s_barrier
	ds_read_b128 v[198:201], v185 offset:49152
	ds_read_b128 v[202:205], v185 offset:50176
	ds_read_b128 v[206:209], v185 offset:51200
	ds_read_b128 v[210:213], v185 offset:52224
	ds_read_b128 v[214:217], v185 offset:53248
	ds_read_b128 v[218:221], v185 offset:54272
	ds_read_b128 v[222:225], v185 offset:55296
	ds_read_b128 v[226:229], v185 offset:56320
	global_load_lds_dwordx4 v[242:243], off
	v_lshl_add_u64 v[140:141], v[140:141], 0, s[44:45]
	s_mov_b32 m0, s24
	s_nop 0
	global_load_lds_dwordx4 v[140:141], off
	s_barrier
	s_waitcnt lgkmcnt(0)
	v_mfma_f32_16x16x32_bf16 v[60:63], v[156:159], v[198:201], v[60:63]
	v_mfma_f32_16x16x32_bf16 v[56:59], v[190:193], v[198:201], v[56:59]
	v_mfma_f32_16x16x32_bf16 v[52:55], v[156:159], v[206:209], v[52:55]
	v_mfma_f32_16x16x32_bf16 v[48:51], v[190:193], v[206:209], v[48:51]
	v_mfma_f32_16x16x32_bf16 v[44:47], v[156:159], v[214:217], v[44:47]
	v_mfma_f32_16x16x32_bf16 v[40:43], v[190:193], v[214:217], v[40:43]
	v_mfma_f32_16x16x32_bf16 v[36:39], v[156:159], v[222:225], v[36:39]
	v_mfma_f32_16x16x32_bf16 v[32:35], v[190:193], v[222:225], v[32:35]
	v_mfma_f32_16x16x32_bf16 v[60:63], v[186:189], v[202:205], v[60:63]
	v_mfma_f32_16x16x32_bf16 v[56:59], v[194:197], v[202:205], v[56:59]
	v_mfma_f32_16x16x32_bf16 v[52:55], v[186:189], v[210:213], v[52:55]
	v_mfma_f32_16x16x32_bf16 v[48:51], v[194:197], v[210:213], v[48:51]
	v_mfma_f32_16x16x32_bf16 v[44:47], v[186:189], v[218:221], v[44:47]
	v_mfma_f32_16x16x32_bf16 v[40:43], v[194:197], v[218:221], v[40:43]
	v_mfma_f32_16x16x32_bf16 v[36:39], v[186:189], v[226:229], v[36:39]
	v_mfma_f32_16x16x32_bf16 v[32:35], v[194:197], v[226:229], v[32:35]
	s_barrier
	s_add_i32 s54, s54, s9
	v_lshl_add_u64 v[140:141], v[160:161], 0, s[44:45]
	s_mov_b32 m0, s54
	v_lshl_add_u64 v[138:139], v[138:139], 0, s[44:45]
	global_load_lds_dwordx4 v[140:141], off
	s_add_i32 m0, s54, 0x2000
	s_nop 0
	global_load_lds_dwordx4 v[138:139], off
	s_waitcnt vmcnt(6)
	s_barrier
	v_mfma_f32_16x16x32_bf16 v[28:31], v[152:155], v[198:201], v[28:31]
	v_mfma_f32_16x16x32_bf16 v[24:27], v[234:237], v[198:201], v[24:27]
	v_mfma_f32_16x16x32_bf16 v[20:23], v[152:155], v[206:209], v[20:23]
	v_mfma_f32_16x16x32_bf16 v[16:19], v[234:237], v[206:209], v[16:19]
	v_mfma_f32_16x16x32_bf16 v[12:15], v[152:155], v[214:217], v[12:15]
	v_mfma_f32_16x16x32_bf16 v[8:11], v[234:237], v[214:217], v[8:11]
	v_mfma_f32_16x16x32_bf16 v[4:7], v[152:155], v[222:225], v[4:7]
	v_mfma_f32_16x16x32_bf16 v[0:3], v[234:237], v[222:225], v[0:3]
	v_mfma_f32_16x16x32_bf16 v[28:31], v[230:233], v[202:205], v[28:31]
	v_mfma_f32_16x16x32_bf16 v[24:27], v[238:241], v[202:205], v[24:27]
	v_mfma_f32_16x16x32_bf16 v[20:23], v[230:233], v[210:213], v[20:23]
	v_mfma_f32_16x16x32_bf16 v[16:19], v[238:241], v[210:213], v[16:19]
	v_mfma_f32_16x16x32_bf16 v[12:15], v[230:233], v[218:221], v[12:15]
	v_mfma_f32_16x16x32_bf16 v[8:11], v[238:241], v[218:221], v[8:11]
	v_mfma_f32_16x16x32_bf16 v[4:7], v[230:233], v[226:229], v[4:7]
	v_mfma_f32_16x16x32_bf16 v[0:3], v[238:241], v[226:229], v[0:3]
	s_add_u32 s34, s34, 0x100
	s_addc_u32 s35, s35, 0
	s_add_u32 s70, s70, 0x100
	s_addc_u32 s71, s71, 0
	s_cmp_ge_i32 s49, s36
	s_cbranch_scc1 .Lrot_exit_1
	s_cmp_eq_u32 s39, s49
	s_cselect_b64 s[54:55], -1, 0
	s_and_b64 vcc, exec, s[54:55]
	v_mov_b64_e32 v[152:153], v[144:145]
	v_mov_b64_e32 v[154:155], v[142:143]
	s_mov_b64 s[88:89], s[68:69]
	s_mov_b64 s[82:83], s[66:67]
	v_mov_b32_e32 v156, v148
	v_mov_b32_e32 v136, v146
	s_mov_b64 s[92:93], s[42:43]
	s_cbranch_vccnz .Lrot_join_1
	v_mov_b64_e32 v[152:153], v[128:129]
	v_mov_b64_e32 v[154:155], v[132:133]
	s_mov_b64 s[88:89], s[12:13]
	s_mov_b64 s[82:83], s[14:15]
	v_mov_b32_e32 v156, v130
	v_mov_b32_e32 v136, v131
	s_mov_b64 s[92:93], s[70:71]

; #define PG8_STAGE(bufoff, gbase, v0, v1) do { \
;         __builtin_amdgcn_global_load_lds((const unsigned*)((const char*)(gbase) + (v0)), (LAS unsigned*)(lds + (bufoff) + ldsw), 16, 0, 0); \
;         __builtin_amdgcn_global_load_lds((const unsigned*)((const char*)(gbase) + (v1)), (LAS unsigned*)(lds + (bufoff) + ldsw + 8192), 16, 0, 0); } while (0)
; #define PG8_LDA(dst, b, h) do { _Pragma("unroll") for (int m = 0; m < 4; ++m) _Pragma("unroll") for (int k = 0; k < 2; ++k) dst[m][k] = *(const LAS bf16x8*)(lds + PG8_SA(b, h) + aoff + m * 2048 + k * 1024); } while (0)
; #define PG8_LDB(dst, b, h) do { _Pragma("unroll") for (int n = 0; n < 2; ++n) _Pragma("unroll") for (int k = 0; k < 2; ++k) dst[n][k] = *(const LAS bf16x8*)(lds + PG8_SB(b, h) + boff + n * 2048 + k * 1024); } while (0)
; #define PG8_MMA(ai, bj, At, Bt) do { __builtin_amdgcn_s_setprio(1); _Pragma("unroll") for (int m = 0; m < 4; ++m) _Pragma("unroll") for (int n = 0; n < 2; ++n) _Pragma("unroll") for (int k = 0; k < 2; ++k) \
;         acc[ai][bj][m][n] = __builtin_amdgcn_mfma_f32_16x16x32_bf16(Bt[n][k], At[m][k], acc[ai][bj][m][n], 0, 0, 0); __builtin_amdgcn_s_setprio(0); } while (0)
; template <class Epi, class Sched>
; __device__ __forceinline__ void gemm_phase(LAS unsigned char* lds, const Sched& S, const Epi& E) {
;     ...
;         for (int t = 0; t < nt; t += 2) {
;             const bool last = (t == nt - 2);
;             const char* a1 = cA + (size_t)(t + 1) * kstep;
;             const char* a2 = last ? nA : cA + (size_t)(t + 2) * kstep; const char* b2 = last ? nB : cB + (size_t)(t + 2) * kstep;
;             const char* a3 = a2 + kstep; const char* b3 = b2 + kstep;
;             const unsigned xA0 = last ? nvA0 : vA0, xA1 = last ? nvA1 : vA1, xB0 = last ? nvB0 : vB0, xB1 = last ? nvB1 : vB1;
;             const size_t xhA = last ? nhA : hA, xhB = last ? nhB : hB;
;             PG8_LDB(B0, 0, 0); PG8_SCHED; PG8_LDA(At, 0, 0); PG8_STAGE(PG8_SA(1, 1), a1 + hA, vA0, vA1);
;             PG8_WAIT_L(8); PG8_BAR; PG8_WAIT_L(0); PG8_MMA(0, 0, At, B0); PG8_BAR; PG8_SCHED;
;             PG8_LDB(B1, 0, 1); PG8_STAGE(PG8_SB(0, 0), b2, xB0, xB1);
;             PG8_BAR; PG8_WAIT_L(0); PG8_MMA(0, 1, At, B1); PG8_BAR;
;             PG8_LDA(At, 0, 1); PG8_STAGE(PG8_SA(0, 0), a2, xA0, xA1);
;             PG8_BAR; PG8_WAIT_L(0); PG8_MMA(1, 0, At, B0); PG8_BAR; PG8_SCHED;
.LBB0_745:
	s_add_u32 s23, s34, 0xfff80080
	s_addc_u32 s71, s35, -1
	s_and_b64 s[42:43], exec, s[42:43]
	s_cselect_b32 s43, s25, s71
	s_cselect_b32 s42, s24, s23
	s_add_i32 s23, 0, 0x10000
	v_add_u32_e32 v138, s23, v147
	ds_read_b128 v[150:153], v138
	ds_read_b128 v[154:157], v138 offset:1024
	ds_read_b128 v[158:161], v138 offset:2048
	ds_read_b128 v[182:185], v138 offset:3072
	v_lshl_add_u64 v[138:139], s[34:35], 0, v[136:137]
	s_add_i32 m0, s50, 0xc000
	ds_read_b128 v[186:189], v148
	ds_read_b128 v[190:193], v148 offset:1024
	ds_read_b128 v[194:197], v148 offset:2048
	ds_read_b128 v[198:201], v148 offset:3072
	ds_read_b128 v[202:205], v148 offset:4096
	ds_read_b128 v[206:209], v148 offset:5120
	ds_read_b128 v[210:213], v148 offset:6144
	ds_read_b128 v[214:217], v148 offset:7168
	global_load_lds_dwordx4 v[138:139], off
	v_lshl_add_u64 v[138:139], s[34:35], 0, v[132:133]
	s_add_i32 m0, s50, 0xe000
	s_nop 0
	global_load_lds_dwordx4 v[138:139], off
	s_waitcnt lgkmcnt(8)
	s_barrier
	s_waitcnt lgkmcnt(0)
	v_mfma_f32_16x16x32_bf16 v[124:127], v[150:153], v[186:189], v[124:127]
	v_mfma_f32_16x16x32_bf16 v[120:123], v[158:161], v[186:189], v[120:123]
	v_mfma_f32_16x16x32_bf16 v[108:111], v[150:153], v[194:197], v[108:111]
	v_mfma_f32_16x16x32_bf16 v[104:107], v[158:161], v[194:197], v[104:107]
	v_mfma_f32_16x16x32_bf16 v[92:95], v[150:153], v[202:205], v[92:95]
	v_mfma_f32_16x16x32_bf16 v[88:91], v[158:161], v[202:205], v[88:91]
	v_mfma_f32_16x16x32_bf16 v[76:79], v[150:153], v[210:213], v[76:79]
	v_mfma_f32_16x16x32_bf16 v[72:75], v[158:161], v[210:213], v[72:75]
	v_mfma_f32_16x16x32_bf16 v[124:127], v[154:157], v[190:193], v[124:127]
	v_mfma_f32_16x16x32_bf16 v[120:123], v[182:185], v[190:193], v[120:123]
	v_mfma_f32_16x16x32_bf16 v[108:111], v[154:157], v[198:201], v[108:111]
	v_mfma_f32_16x16x32_bf16 v[104:107], v[182:185], v[198:201], v[104:107]
	v_mfma_f32_16x16x32_bf16 v[92:95], v[154:157], v[206:209], v[92:95]
	v_mfma_f32_16x16x32_bf16 v[88:91], v[182:185], v[206:209], v[88:91]
	v_mfma_f32_16x16x32_bf16 v[76:79], v[154:157], v[214:217], v[76:79]
	v_mfma_f32_16x16x32_bf16 v[72:75], v[182:185], v[214:217], v[72:75]
	s_barrier
	s_add_i32 s71, 0, 0x14000
	v_add_u32_e32 v138, s71, v147
	s_add_i32 s23, s23, s49
	ds_read_b128 v[218:221], v138
	ds_read_b128 v[222:225], v138 offset:1024
	ds_read_b128 v[226:229], v138 offset:2048
	ds_read_b128 v[230:233], v138 offset:3072
	v_lshl_add_u64 v[138:139], s[40:41], 0, v[142:143]
	s_mov_b32 m0, s23
	v_lshl_add_u64 v[140:141], s[40:41], 0, v[134:135]
	global_load_lds_dwordx4 v[138:139], off
	s_add_i32 m0, s23, 0x2000
	s_nop 0
	global_load_lds_dwordx4 v[140:141], off
	s_barrier
	s_waitcnt lgkmcnt(0)
	v_mfma_f32_16x16x32_bf16 v[116:119], v[218:221], v[186:189], v[116:119]
	v_mfma_f32_16x16x32_bf16 v[112:115], v[226:229], v[186:189], v[112:115]
	v_mfma_f32_16x16x32_bf16 v[100:103], v[218:221], v[194:197], v[100:103]
	v_mfma_f32_16x16x32_bf16 v[96:99], v[226:229], v[194:197], v[96:99]
	v_mfma_f32_16x16x32_bf16 v[84:87], v[218:221], v[202:205], v[84:87]
	v_mfma_f32_16x16x32_bf16 v[80:83], v[226:229], v[202:205], v[80:83]
	v_mfma_f32_16x16x32_bf16 v[68:71], v[218:221], v[210:213], v[68:71]
	v_mfma_f32_16x16x32_bf16 v[64:67], v[226:229], v[210:213], v[64:67]
	v_mfma_f32_16x16x32_bf16 v[116:119], v[222:225], v[190:193], v[116:119]
	v_mfma_f32_16x16x32_bf16 v[112:115], v[230:233], v[190:193], v[112:115]
	v_mfma_f32_16x16x32_bf16 v[100:103], v[222:225], v[198:201], v[100:103]
	v_mfma_f32_16x16x32_bf16 v[96:99], v[230:233], v[198:201], v[96:99]
	v_mfma_f32_16x16x32_bf16 v[84:87], v[222:225], v[206:209], v[84:87]
	v_mfma_f32_16x16x32_bf16 v[80:83], v[230:233], v[206:209], v[80:83]
	v_mfma_f32_16x16x32_bf16 v[68:71], v[222:225], v[214:217], v[68:71]
	v_mfma_f32_16x16x32_bf16 v[64:67], v[230:233], v[214:217], v[64:67]
	s_mov_b32 m0, s50
	v_lshl_add_u64 v[234:235], s[42:43], 0, v[142:143]
	s_barrier
	ds_read_b128 v[186:189], v148 offset:16384
	ds_read_b128 v[190:193], v148 offset:17408
	ds_read_b128 v[194:197], v148 offset:18432
	ds_read_b128 v[198:201], v148 offset:19456
	ds_read_b128 v[202:205], v148 offset:20480
	ds_read_b128 v[206:209], v148 offset:21504
	ds_read_b128 v[210:213], v148 offset:22528
	ds_read_b128 v[214:217], v148 offset:23552
	global_load_lds_dwordx4 v[234:235], off
	v_lshl_add_u64 v[236:237], s[42:43], 0, v[134:135]
	s_mov_b32 m0, s51
	s_nop 0
	global_load_lds_dwordx4 v[236:237], off
	s_barrier
	s_waitcnt lgkmcnt(0)
	v_mfma_f32_16x16x32_bf16 v[60:63], v[150:153], v[186:189], v[60:63]
	v_mfma_f32_16x16x32_bf16 v[56:59], v[158:161], v[186:189], v[56:59]
	v_mfma_f32_16x16x32_bf16 v[44:47], v[150:153], v[194:197], v[44:47]
	v_mfma_f32_16x16x32_bf16 v[40:43], v[158:161], v[194:197], v[40:43]
	v_mfma_f32_16x16x32_bf16 v[28:31], v[150:153], v[202:205], v[28:31]
	v_mfma_f32_16x16x32_bf16 v[24:27], v[158:161], v[202:205], v[24:27]
	v_mfma_f32_16x16x32_bf16 v[12:15], v[150:153], v[210:213], v[12:15]
	v_mfma_f32_16x16x32_bf16 v[8:11], v[158:161], v[210:213], v[8:11]
	v_mfma_f32_16x16x32_bf16 v[60:63], v[154:157], v[190:193], v[60:63]
	v_mfma_f32_16x16x32_bf16 v[56:59], v[182:185], v[190:193], v[56:59]
	v_mfma_f32_16x16x32_bf16 v[44:47], v[154:157], v[198:201], v[44:47]
	v_mfma_f32_16x16x32_bf16 v[40:43], v[182:185], v[198:201], v[40:43]
	v_mfma_f32_16x16x32_bf16 v[28:31], v[154:157], v[206:209], v[28:31]
	v_mfma_f32_16x16x32_bf16 v[24:27], v[182:185], v[206:209], v[24:27]
	v_mfma_f32_16x16x32_bf16 v[12:15], v[154:157], v[214:217], v[12:15]
	v_mfma_f32_16x16x32_bf16 v[8:11], v[182:185], v[214:217], v[8:11]
	s_barrier
; #define PG8_STAGE(bufoff, gbase, v0, v1) do { \
;         __builtin_amdgcn_global_load_lds((const unsigned*)((const char*)(gbase) + (v0)), (LAS unsigned*)(lds + (bufoff) + ldsw), 16, 0, 0); \
;         __builtin_amdgcn_global_load_lds((const unsigned*)((const char*)(gbase) + (v1)), (LAS unsigned*)(lds + (bufoff) + ldsw + 8192), 16, 0, 0); } while (0)
; #define PG8_LDA(dst, b, h) do { _Pragma("unroll") for (int m = 0; m < 4; ++m) _Pragma("unroll") for (int k = 0; k < 2; ++k) dst[m][k] = *(const LAS bf16x8*)(lds + PG8_SA(b, h) + aoff + m * 2048 + k * 1024); } while (0)
; #define PG8_LDB(dst, b, h) do { _Pragma("unroll") for (int n = 0; n < 2; ++n) _Pragma("unroll") for (int k = 0; k < 2; ++k) dst[n][k] = *(const LAS bf16x8*)(lds + PG8_SB(b, h) + boff + n * 2048 + k * 1024); } while (0)
; #define PG8_MMA(ai, bj, At, Bt) do { __builtin_amdgcn_s_setprio(1); _Pragma("unroll") for (int m = 0; m < 4; ++m) _Pragma("unroll") for (int n = 0; n < 2; ++n) _Pragma("unroll") for (int k = 0; k < 2; ++k) \
;         acc[ai][bj][m][n] = __builtin_amdgcn_mfma_f32_16x16x32_bf16(Bt[n][k], At[m][k], acc[ai][bj][m][n], 0, 0, 0); __builtin_amdgcn_s_setprio(0); } while (0)
; #define PG8_WAIT_V(n) asm volatile("s_waitcnt vmcnt(" #n ")" ::: "memory")
; #define PG8_WAIT_L(n) asm volatile("s_waitcnt lgkmcnt(" #n ")" ::: "memory")
; #define PG8_BAR __builtin_amdgcn_s_barrier()
; #define PG8_SCHED __builtin_amdgcn_sched_barrier(0)
; template <class Epi, class Sched>
; __device__ __forceinline__ void gemm_phase(LAS unsigned char* lds, const Sched& S, const Epi& E) {
;     ...
;             PG8_STAGE(PG8_SB(0, 1), b2 + xhB, xB0, xB1);
;             PG8_WAIT_V(6); PG8_BAR; PG8_MMA(1, 1, At, B1); PG8_BAR;
;             PG8_LDB(B0, 1, 0); PG8_SCHED; PG8_LDA(At, 1, 0); PG8_STAGE(PG8_SA(0, 1), a2 + xhA, xA0, xA1);
;             PG8_WAIT_L(8); PG8_BAR; PG8_WAIT_L(0); PG8_MMA(0, 0, At, B0); PG8_BAR; PG8_SCHED;
;             PG8_LDB(B1, 1, 1); PG8_STAGE(PG8_SB(1, 0), b3, xB0, xB1);
;             PG8_BAR; PG8_WAIT_L(0); PG8_MMA(0, 1, At, B1); PG8_BAR;
	s_add_u32 s82, s40, 0x80000
	s_addc_u32 s83, s41, 0
	s_add_i32 s23, s71, s49
	v_lshl_add_u64 v[150:151], s[82:83], 0, v[142:143]
	s_mov_b32 m0, s23
	s_nop 0
	global_load_lds_dwordx4 v[150:151], off
	v_lshl_add_u64 v[150:151], s[82:83], 0, v[134:135]
	s_add_i32 m0, s23, 0x2000
	s_nop 0
	global_load_lds_dwordx4 v[150:151], off
	s_waitcnt vmcnt(6)
	s_barrier
	v_mfma_f32_16x16x32_bf16 v[52:55], v[218:221], v[186:189], v[52:55]
	v_mfma_f32_16x16x32_bf16 v[48:51], v[226:229], v[186:189], v[48:51]
	v_mfma_f32_16x16x32_bf16 v[36:39], v[218:221], v[194:197], v[36:39]
	v_mfma_f32_16x16x32_bf16 v[32:35], v[226:229], v[194:197], v[32:35]
	v_mfma_f32_16x16x32_bf16 v[20:23], v[218:221], v[202:205], v[20:23]
	v_mfma_f32_16x16x32_bf16 v[16:19], v[226:229], v[202:205], v[16:19]
	v_mfma_f32_16x16x32_bf16 v[4:7], v[218:221], v[210:213], v[4:7]
	v_mfma_f32_16x16x32_bf16 v[0:3], v[226:229], v[210:213], v[0:3]
	v_mfma_f32_16x16x32_bf16 v[52:55], v[222:225], v[190:193], v[52:55]
	v_mfma_f32_16x16x32_bf16 v[48:51], v[230:233], v[190:193], v[48:51]
	v_mfma_f32_16x16x32_bf16 v[36:39], v[222:225], v[198:201], v[36:39]
	v_mfma_f32_16x16x32_bf16 v[32:35], v[230:233], v[198:201], v[32:35]
	v_mfma_f32_16x16x32_bf16 v[20:23], v[222:225], v[206:209], v[20:23]
	v_mfma_f32_16x16x32_bf16 v[16:19], v[230:233], v[206:209], v[16:19]
	v_mfma_f32_16x16x32_bf16 v[4:7], v[222:225], v[214:217], v[4:7]
	v_mfma_f32_16x16x32_bf16 v[0:3], v[230:233], v[214:217], v[0:3]
	s_add_i32 s23, 0, 0x18000
	v_add_u32_e32 v149, s23, v147
	s_barrier
	ds_read_b128 v[150:153], v149
	ds_read_b128 v[154:157], v149 offset:1024
	ds_read_b128 v[158:161], v149 offset:2048
	ds_read_b128 v[182:185], v149 offset:3072
	s_add_u32 s42, s42, 0x80000
	s_addc_u32 s43, s43, 0
	s_mov_b32 m0, s54
	v_lshl_add_u64 v[218:219], s[42:43], 0, v[142:143]
	ds_read_b128 v[186:189], v148 offset:32768
	ds_read_b128 v[190:193], v148 offset:33792
	ds_read_b128 v[194:197], v148 offset:34816
	ds_read_b128 v[198:201], v148 offset:35840
	ds_read_b128 v[202:205], v148 offset:36864
	ds_read_b128 v[206:209], v148 offset:37888
	ds_read_b128 v[210:213], v148 offset:38912
	ds_read_b128 v[214:217], v148 offset:39936
	global_load_lds_dwordx4 v[218:219], off
	v_lshl_add_u64 v[218:219], s[42:43], 0, v[134:135]
	s_mov_b32 m0, s55
	s_nop 0
	global_load_lds_dwordx4 v[218:219], off
	s_waitcnt lgkmcnt(8)
	s_barrier
	s_waitcnt lgkmcnt(0)
	v_mfma_f32_16x16x32_bf16 v[124:127], v[150:153], v[186:189], v[124:127]
	v_mfma_f32_16x16x32_bf16 v[120:123], v[158:161], v[186:189], v[120:123]
	v_mfma_f32_16x16x32_bf16 v[108:111], v[150:153], v[194:197], v[108:111]
	v_mfma_f32_16x16x32_bf16 v[104:107], v[158:161], v[194:197], v[104:107]
	v_mfma_f32_16x16x32_bf16 v[92:95], v[150:153], v[202:205], v[92:95]
	v_mfma_f32_16x16x32_bf16 v[88:91], v[158:161], v[202:205], v[88:91]
	v_mfma_f32_16x16x32_bf16 v[76:79], v[150:153], v[210:213], v[76:79]
	v_mfma_f32_16x16x32_bf16 v[72:75], v[158:161], v[210:213], v[72:75]
	v_mfma_f32_16x16x32_bf16 v[124:127], v[154:157], v[190:193], v[124:127]
	v_mfma_f32_16x16x32_bf16 v[120:123], v[182:185], v[190:193], v[120:123]
	v_mfma_f32_16x16x32_bf16 v[108:111], v[154:157], v[198:201], v[108:111]
	v_mfma_f32_16x16x32_bf16 v[104:107], v[182:185], v[198:201], v[104:107]
	v_mfma_f32_16x16x32_bf16 v[92:95], v[154:157], v[206:209], v[92:95]
	v_mfma_f32_16x16x32_bf16 v[88:91], v[182:185], v[206:209], v[88:91]
	v_mfma_f32_16x16x32_bf16 v[76:79], v[154:157], v[214:217], v[76:79]
	v_mfma_f32_16x16x32_bf16 v[72:75], v[182:185], v[214:217], v[72:75]
	s_barrier
	s_add_i32 s42, 0, 0x1c000
	s_add_i32 s23, s23, s49
	v_add_u32_e32 v149, s42, v147
	v_lshl_add_u64 v[138:139], v[138:139], 0, s[44:45]
	s_mov_b32 m0, s23
	ds_read_b128 v[218:221], v149
	ds_read_b128 v[222:225], v149 offset:1024
	ds_read_b128 v[226:229], v149 offset:2048
	ds_read_b128 v[230:233], v149 offset:3072
	global_load_lds_dwordx4 v[138:139], off
	v_lshl_add_u64 v[138:139], v[140:141], 0, s[44:45]
	s_add_i32 m0, s23, 0x2000
	s_nop 0
	global_load_lds_dwordx4 v[138:139], off
	s_barrier
; #define PG8_STAGE(bufoff, gbase, v0, v1) do { \
;         __builtin_amdgcn_global_load_lds((const unsigned*)((const char*)(gbase) + (v0)), (LAS unsigned*)(lds + (bufoff) + ldsw), 16, 0, 0); \
;         __builtin_amdgcn_global_load_lds((const unsigned*)((const char*)(gbase) + (v1)), (LAS unsigned*)(lds + (bufoff) + ldsw + 8192), 16, 0, 0); } while (0)
; #define PG8_LDA(dst, b, h) do { _Pragma("unroll") for (int m = 0; m < 4; ++m) _Pragma("unroll") for (int k = 0; k < 2; ++k) dst[m][k] = *(const LAS bf16x8*)(lds + PG8_SA(b, h) + aoff + m * 2048 + k * 1024); } while (0)
; #define PG8_MMA(ai, bj, At, Bt) do { __builtin_amdgcn_s_setprio(1); _Pragma("unroll") for (int m = 0; m < 4; ++m) _Pragma("unroll") for (int n = 0; n < 2; ++n) _Pragma("unroll") for (int k = 0; k < 2; ++k) \
;         acc[ai][bj][m][n] = __builtin_amdgcn_mfma_f32_16x16x32_bf16(Bt[n][k], At[m][k], acc[ai][bj][m][n], 0, 0, 0); __builtin_amdgcn_s_setprio(0); } while (0)
; #define PG8_WAIT_V(n) asm volatile("s_waitcnt vmcnt(" #n ")" ::: "memory")
; #define PG8_WAIT_L(n) asm volatile("s_waitcnt lgkmcnt(" #n ")" ::: "memory")
; #define PG8_BAR __builtin_amdgcn_s_barrier()
; #define PG8_SCHED __builtin_amdgcn_sched_barrier(0)
; template <class Epi, class Sched>
; __device__ __forceinline__ void gemm_phase(LAS unsigned char* lds, const Sched& S, const Epi& E) {
;     ...
;             const bool last = (t == nt - 2);
;             const char* a1 = cA + (size_t)(t + 1) * kstep;
;             const char* a2 = last ? nA : cA + (size_t)(t + 2) * kstep; const char* b2 = last ? nB : cB + (size_t)(t + 2) * kstep;
;             const char* a3 = a2 + kstep; const char* b3 = b2 + kstep;
;             const unsigned xA0 = last ? nvA0 : vA0, xA1 = last ? nvA1 : vA1, xB0 = last ? nvB0 : vB0, xB1 = last ? nvB1 : vB1;
;             const size_t xhA = last ? nhA : hA, xhB = last ? nhB : hB;
;     ...
;             PG8_BAR; PG8_WAIT_L(0); PG8_MMA(0, 1, At, B1); PG8_BAR;
;             PG8_LDA(At, 1, 1); PG8_STAGE(PG8_SA(1, 0), a3, xA0, xA1);
;             PG8_BAR; PG8_WAIT_L(0); PG8_MMA(1, 0, At, B0); PG8_BAR; PG8_SCHED;
;             PG8_STAGE(PG8_SB(1, 1), b3 + xhB, xB0, xB1);
;             PG8_WAIT_V(6); PG8_BAR; PG8_MMA(1, 1, At, B1); PG8_BAR;
;         }
	s_waitcnt lgkmcnt(0)
	v_mfma_f32_16x16x32_bf16 v[116:119], v[218:221], v[186:189], v[116:119]
	v_mfma_f32_16x16x32_bf16 v[112:115], v[226:229], v[186:189], v[112:115]
	v_mfma_f32_16x16x32_bf16 v[100:103], v[218:221], v[194:197], v[100:103]
	v_mfma_f32_16x16x32_bf16 v[96:99], v[226:229], v[194:197], v[96:99]
	v_mfma_f32_16x16x32_bf16 v[84:87], v[218:221], v[202:205], v[84:87]
	v_mfma_f32_16x16x32_bf16 v[80:83], v[226:229], v[202:205], v[80:83]
	v_mfma_f32_16x16x32_bf16 v[68:71], v[218:221], v[210:213], v[68:71]
	v_mfma_f32_16x16x32_bf16 v[64:67], v[226:229], v[210:213], v[64:67]
	v_mfma_f32_16x16x32_bf16 v[116:119], v[222:225], v[190:193], v[116:119]
	v_mfma_f32_16x16x32_bf16 v[112:115], v[230:233], v[190:193], v[112:115]
	v_mfma_f32_16x16x32_bf16 v[100:103], v[222:225], v[198:201], v[100:103]
	v_mfma_f32_16x16x32_bf16 v[96:99], v[230:233], v[198:201], v[96:99]
	v_mfma_f32_16x16x32_bf16 v[84:87], v[222:225], v[206:209], v[84:87]
	v_mfma_f32_16x16x32_bf16 v[80:83], v[230:233], v[206:209], v[80:83]
	v_mfma_f32_16x16x32_bf16 v[68:71], v[222:225], v[214:217], v[68:71]
	v_mfma_f32_16x16x32_bf16 v[64:67], v[230:233], v[214:217], v[64:67]
	s_mov_b32 m0, s66
	v_lshl_add_u64 v[138:139], v[234:235], 0, s[44:45]
	s_barrier
	ds_read_b128 v[186:189], v148 offset:49152
	ds_read_b128 v[190:193], v148 offset:50176
	ds_read_b128 v[194:197], v148 offset:51200
	ds_read_b128 v[198:201], v148 offset:52224
	ds_read_b128 v[202:205], v148 offset:53248
	ds_read_b128 v[206:209], v148 offset:54272
	ds_read_b128 v[210:213], v148 offset:55296
	ds_read_b128 v[214:217], v148 offset:56320
	global_load_lds_dwordx4 v[138:139], off
	v_lshl_add_u64 v[138:139], v[236:237], 0, s[44:45]
	s_mov_b32 m0, s67
	s_nop 0
	global_load_lds_dwordx4 v[138:139], off
	s_barrier
	s_waitcnt lgkmcnt(0)
	v_mfma_f32_16x16x32_bf16 v[60:63], v[150:153], v[186:189], v[60:63]
	v_mfma_f32_16x16x32_bf16 v[56:59], v[158:161], v[186:189], v[56:59]
	v_mfma_f32_16x16x32_bf16 v[44:47], v[150:153], v[194:197], v[44:47]
	v_mfma_f32_16x16x32_bf16 v[40:43], v[158:161], v[194:197], v[40:43]
	v_mfma_f32_16x16x32_bf16 v[28:31], v[150:153], v[202:205], v[28:31]
	v_mfma_f32_16x16x32_bf16 v[24:27], v[158:161], v[202:205], v[24:27]
	v_mfma_f32_16x16x32_bf16 v[12:15], v[150:153], v[210:213], v[12:15]
	v_mfma_f32_16x16x32_bf16 v[8:11], v[158:161], v[210:213], v[8:11]
	v_mfma_f32_16x16x32_bf16 v[60:63], v[154:157], v[190:193], v[60:63]
	v_mfma_f32_16x16x32_bf16 v[56:59], v[182:185], v[190:193], v[56:59]
	v_mfma_f32_16x16x32_bf16 v[44:47], v[154:157], v[198:201], v[44:47]
	v_mfma_f32_16x16x32_bf16 v[40:43], v[182:185], v[198:201], v[40:43]
	v_mfma_f32_16x16x32_bf16 v[28:31], v[154:157], v[206:209], v[28:31]
	v_mfma_f32_16x16x32_bf16 v[24:27], v[182:185], v[206:209], v[24:27]
	v_mfma_f32_16x16x32_bf16 v[12:15], v[154:157], v[214:217], v[12:15]
	v_mfma_f32_16x16x32_bf16 v[8:11], v[182:185], v[214:217], v[8:11]
	s_barrier
	s_add_u32 s40, s40, 0x80080
	s_addc_u32 s41, s41, 0
	s_add_i32 s23, s42, s49
	v_lshl_add_u64 v[138:139], s[40:41], 0, v[142:143]
	s_mov_b32 m0, s23
	v_lshl_add_u64 v[134:135], s[40:41], 0, v[134:135]
	global_load_lds_dwordx4 v[138:139], off
	s_add_i32 m0, s23, 0x2000
	s_nop 0
	global_load_lds_dwordx4 v[134:135], off
	s_waitcnt vmcnt(6)
	s_barrier
	v_mfma_f32_16x16x32_bf16 v[52:55], v[218:221], v[186:189], v[52:55]
	v_mfma_f32_16x16x32_bf16 v[48:51], v[226:229], v[186:189], v[48:51]
	v_mfma_f32_16x16x32_bf16 v[36:39], v[218:221], v[194:197], v[36:39]
	v_mfma_f32_16x16x32_bf16 v[32:35], v[226:229], v[194:197], v[32:35]
	v_mfma_f32_16x16x32_bf16 v[20:23], v[218:221], v[202:205], v[20:23]
	v_mfma_f32_16x16x32_bf16 v[16:19], v[226:229], v[202:205], v[16:19]
	v_mfma_f32_16x16x32_bf16 v[4:7], v[218:221], v[210:213], v[4:7]
	v_mfma_f32_16x16x32_bf16 v[0:3], v[226:229], v[210:213], v[0:3]
	v_mfma_f32_16x16x32_bf16 v[52:55], v[222:225], v[190:193], v[52:55]
	v_mfma_f32_16x16x32_bf16 v[48:51], v[230:233], v[190:193], v[48:51]
	v_mfma_f32_16x16x32_bf16 v[36:39], v[222:225], v[198:201], v[36:39]
	v_mfma_f32_16x16x32_bf16 v[32:35], v[230:233], v[198:201], v[32:35]
	v_mfma_f32_16x16x32_bf16 v[20:23], v[222:225], v[206:209], v[20:23]
	v_mfma_f32_16x16x32_bf16 v[16:19], v[230:233], v[206:209], v[16:19]
	v_mfma_f32_16x16x32_bf16 v[4:7], v[222:225], v[214:217], v[4:7]
	v_mfma_f32_16x16x32_bf16 v[0:3], v[230:233], v[214:217], v[0:3]
	s_add_i32 s21, s21, 2
	s_add_u32 s34, s34, 0x100
	s_addc_u32 s35, s35, 0
	s_add_u32 s38, s38, 0x100
	s_addc_u32 s39, s39, 0
	s_cmp_gt_u32 s21, 29
	s_cbranch_scc1 .Lrot_exit_2
	s_cmp_eq_u32 s21, 28
	s_cselect_b64 s[42:43], -1, 0
	s_and_b64 vcc, exec, s[42:43]
	v_mov_b64_e32 v[134:135], v[130:131]
	v_mov_b64_e32 v[142:143], v[128:129]
	s_mov_b64 s[40:41], s[26:27]
	s_cbranch_vccnz .Lrot_join_2
	v_mov_b64_e32 v[134:135], v[132:133]
	v_mov_b64_e32 v[142:143], v[136:137]
	s_mov_b64 s[40:41], s[38:39]

; #define PG8_STAGE(bufoff, gbase, v0, v1) do { \
;         __builtin_amdgcn_global_load_lds((const unsigned*)((const char*)(gbase) + (v0)), (LAS unsigned*)(lds + (bufoff) + ldsw), 16, 0, 0); \
;         __builtin_amdgcn_global_load_lds((const unsigned*)((const char*)(gbase) + (v1)), (LAS unsigned*)(lds + (bufoff) + ldsw + 8192), 16, 0, 0); } while (0)
; #define PG8_LDA(dst, b, h) do { _Pragma("unroll") for (int m = 0; m < 4; ++m) _Pragma("unroll") for (int k = 0; k < 2; ++k) dst[m][k] = *(const LAS bf16x8*)(lds + PG8_SA(b, h) + aoff + m * 2048 + k * 1024); } while (0)
; #define PG8_LDB(dst, b, h) do { _Pragma("unroll") for (int n = 0; n < 2; ++n) _Pragma("unroll") for (int k = 0; k < 2; ++k) dst[n][k] = *(const LAS bf16x8*)(lds + PG8_SB(b, h) + boff + n * 2048 + k * 1024); } while (0)
; #define PG8_MMA(ai, bj, At, Bt) do { __builtin_amdgcn_s_setprio(1); _Pragma("unroll") for (int m = 0; m < 4; ++m) _Pragma("unroll") for (int n = 0; n < 2; ++n) _Pragma("unroll") for (int k = 0; k < 2; ++k) \
;         acc[ai][bj][m][n] = __builtin_amdgcn_mfma_f32_16x16x32_bf16(Bt[n][k], At[m][k], acc[ai][bj][m][n], 0, 0, 0); __builtin_amdgcn_s_setprio(0); } while (0)
; template <class Epi, class Sched>
; __device__ __forceinline__ void gemm_phase(LAS unsigned char* lds, const Sched& S, const Epi& E) {
;     ...
;         for (int t = 0; t < nt; t += 2) {
;             const bool last = (t == nt - 2);
;             const char* a1 = cA + (size_t)(t + 1) * kstep;
;             const char* a2 = last ? nA : cA + (size_t)(t + 2) * kstep; const char* b2 = last ? nB : cB + (size_t)(t + 2) * kstep;
;             const char* a3 = a2 + kstep; const char* b3 = b2 + kstep;
;             const unsigned xA0 = last ? nvA0 : vA0, xA1 = last ? nvA1 : vA1, xB0 = last ? nvB0 : vB0, xB1 = last ? nvB1 : vB1;
;             const size_t xhA = last ? nhA : hA, xhB = last ? nhB : hB;
;             PG8_LDB(B0, 0, 0); PG8_SCHED; PG8_LDA(At, 0, 0); PG8_STAGE(PG8_SA(1, 1), a1 + hA, vA0, vA1);
;             PG8_WAIT_L(8); PG8_BAR; PG8_WAIT_L(0); PG8_MMA(0, 0, At, B0); PG8_BAR; PG8_SCHED;
;             PG8_LDB(B1, 0, 1); PG8_STAGE(PG8_SB(0, 0), b2, xB0, xB1);
;             PG8_BAR; PG8_WAIT_L(0); PG8_MMA(0, 1, At, B1); PG8_BAR;
;             PG8_LDA(At, 0, 1); PG8_STAGE(PG8_SA(0, 0), a2, xA0, xA1);
;             PG8_BAR; PG8_WAIT_L(0); PG8_MMA(1, 0, At, B0); PG8_BAR; PG8_SCHED;
.LBB0_808:
	s_add_u32 s21, s26, 0xfff80080
	s_addc_u32 s69, s27, -1
	s_and_b64 s[40:41], exec, s[40:41]
	s_cselect_b32 s41, s23, s69
	s_cselect_b32 s40, s22, s21
	s_add_i32 s21, 0, 0x10000
	v_add_u32_e32 v138, s21, v155
	ds_read_b128 v[158:161], v138
	ds_read_b128 v[182:185], v138 offset:1024
	ds_read_b128 v[186:189], v138 offset:2048
	ds_read_b128 v[190:193], v138 offset:3072
	v_lshl_add_u64 v[138:139], s[26:27], 0, v[132:133]
	s_add_i32 m0, s48, 0xc000
	ds_read_b128 v[194:197], v143
	ds_read_b128 v[198:201], v143 offset:1024
	ds_read_b128 v[202:205], v143 offset:2048
	ds_read_b128 v[206:209], v143 offset:3072
	ds_read_b128 v[210:213], v143 offset:4096
	ds_read_b128 v[214:217], v143 offset:5120
	ds_read_b128 v[218:221], v143 offset:6144
	ds_read_b128 v[222:225], v143 offset:7168
	global_load_lds_dwordx4 v[138:139], off
	v_lshl_add_u64 v[138:139], s[26:27], 0, v[134:135]
	s_add_i32 m0, s48, 0xe000
	s_nop 0
	global_load_lds_dwordx4 v[138:139], off
	s_waitcnt lgkmcnt(8)
	s_barrier
	s_waitcnt lgkmcnt(0)
	v_mfma_f32_16x16x32_bf16 v[124:127], v[158:161], v[194:197], v[124:127]
	v_mfma_f32_16x16x32_bf16 v[120:123], v[186:189], v[194:197], v[120:123]
	v_mfma_f32_16x16x32_bf16 v[112:115], v[158:161], v[202:205], v[112:115]
	v_mfma_f32_16x16x32_bf16 v[104:107], v[186:189], v[202:205], v[104:107]
	v_mfma_f32_16x16x32_bf16 v[96:99], v[158:161], v[210:213], v[96:99]
	v_mfma_f32_16x16x32_bf16 v[88:91], v[186:189], v[210:213], v[88:91]
	v_mfma_f32_16x16x32_bf16 v[80:83], v[158:161], v[218:221], v[80:83]
	v_mfma_f32_16x16x32_bf16 v[72:75], v[186:189], v[218:221], v[72:75]
	v_mfma_f32_16x16x32_bf16 v[124:127], v[182:185], v[198:201], v[124:127]
	v_mfma_f32_16x16x32_bf16 v[120:123], v[190:193], v[198:201], v[120:123]
	v_mfma_f32_16x16x32_bf16 v[112:115], v[182:185], v[206:209], v[112:115]
	v_mfma_f32_16x16x32_bf16 v[104:107], v[190:193], v[206:209], v[104:107]
	v_mfma_f32_16x16x32_bf16 v[96:99], v[182:185], v[214:217], v[96:99]
	v_mfma_f32_16x16x32_bf16 v[88:91], v[190:193], v[214:217], v[88:91]
	v_mfma_f32_16x16x32_bf16 v[80:83], v[182:185], v[222:225], v[80:83]
	v_mfma_f32_16x16x32_bf16 v[72:75], v[190:193], v[222:225], v[72:75]
	s_barrier
	s_add_i32 s69, 0, 0x14000
	s_add_i32 s21, s21, s43
	v_add_u32_e32 v138, s69, v155
	s_mov_b32 m0, s21
	ds_read_b128 v[226:229], v138
	ds_read_b128 v[230:233], v138 offset:1024
	ds_read_b128 v[234:237], v138 offset:2048
	ds_read_b128 v[238:241], v138 offset:3072
	global_load_lds_dwordx4 v136, s[38:39]
	s_add_i32 m0, s21, 0x2000
	v_mov_b32_e32 v147, v137
	global_load_lds_dwordx4 v146, s[38:39]
	s_barrier
	s_waitcnt lgkmcnt(0)
	v_lshl_add_u64 v[138:139], s[38:39], 0, v[136:137]
	v_lshl_add_u64 v[140:141], s[38:39], 0, v[146:147]
	v_mfma_f32_16x16x32_bf16 v[116:119], v[226:229], v[194:197], v[116:119]
	v_mfma_f32_16x16x32_bf16 v[108:111], v[234:237], v[194:197], v[108:111]
	v_mfma_f32_16x16x32_bf16 v[100:103], v[226:229], v[202:205], v[100:103]
	v_mfma_f32_16x16x32_bf16 v[92:95], v[234:237], v[202:205], v[92:95]
	v_mfma_f32_16x16x32_bf16 v[84:87], v[226:229], v[210:213], v[84:87]
	v_mfma_f32_16x16x32_bf16 v[76:79], v[234:237], v[210:213], v[76:79]
	v_mfma_f32_16x16x32_bf16 v[68:71], v[226:229], v[218:221], v[68:71]
	v_mfma_f32_16x16x32_bf16 v[64:67], v[234:237], v[218:221], v[64:67]
	v_mfma_f32_16x16x32_bf16 v[116:119], v[230:233], v[198:201], v[116:119]
	v_mfma_f32_16x16x32_bf16 v[108:111], v[238:241], v[198:201], v[108:111]
	v_mfma_f32_16x16x32_bf16 v[100:103], v[230:233], v[206:209], v[100:103]
	v_mfma_f32_16x16x32_bf16 v[92:95], v[238:241], v[206:209], v[92:95]
	v_mfma_f32_16x16x32_bf16 v[84:87], v[230:233], v[214:217], v[84:87]
	v_mfma_f32_16x16x32_bf16 v[76:79], v[238:241], v[214:217], v[76:79]
	v_mfma_f32_16x16x32_bf16 v[68:71], v[230:233], v[222:225], v[68:71]
	v_mfma_f32_16x16x32_bf16 v[64:67], v[238:241], v[222:225], v[64:67]
	s_mov_b32 m0, s48
	v_lshl_add_u64 v[242:243], s[40:41], 0, v[150:151]
	s_barrier
	ds_read_b128 v[194:197], v143 offset:16384
	ds_read_b128 v[198:201], v143 offset:17408
	ds_read_b128 v[202:205], v143 offset:18432
	ds_read_b128 v[206:209], v143 offset:19456
	ds_read_b128 v[210:213], v143 offset:20480
	ds_read_b128 v[214:217], v143 offset:21504
	ds_read_b128 v[218:221], v143 offset:22528
	ds_read_b128 v[222:225], v143 offset:23552
	global_load_lds_dwordx4 v[242:243], off
	v_lshl_add_u64 v[244:245], s[40:41], 0, v[148:149]
	s_mov_b32 m0, s49
	s_nop 0
	global_load_lds_dwordx4 v[244:245], off
	s_barrier
	s_waitcnt lgkmcnt(0)
	v_mfma_f32_16x16x32_bf16 v[60:63], v[158:161], v[194:197], v[60:63]
	v_mfma_f32_16x16x32_bf16 v[56:59], v[186:189], v[194:197], v[56:59]
	v_mfma_f32_16x16x32_bf16 v[44:47], v[158:161], v[202:205], v[44:47]
	v_mfma_f32_16x16x32_bf16 v[40:43], v[186:189], v[202:205], v[40:43]
	v_mfma_f32_16x16x32_bf16 v[28:31], v[158:161], v[210:213], v[28:31]
	v_mfma_f32_16x16x32_bf16 v[24:27], v[186:189], v[210:213], v[24:27]
	v_mfma_f32_16x16x32_bf16 v[12:15], v[158:161], v[218:221], v[12:15]
	v_mfma_f32_16x16x32_bf16 v[8:11], v[186:189], v[218:221], v[8:11]
	v_mfma_f32_16x16x32_bf16 v[60:63], v[182:185], v[198:201], v[60:63]
	v_mfma_f32_16x16x32_bf16 v[56:59], v[190:193], v[198:201], v[56:59]
	v_mfma_f32_16x16x32_bf16 v[44:47], v[182:185], v[206:209], v[44:47]
	v_mfma_f32_16x16x32_bf16 v[40:43], v[190:193], v[206:209], v[40:43]
	v_mfma_f32_16x16x32_bf16 v[28:31], v[182:185], v[214:217], v[28:31]
	v_mfma_f32_16x16x32_bf16 v[24:27], v[190:193], v[214:217], v[24:27]
	v_mfma_f32_16x16x32_bf16 v[12:15], v[182:185], v[222:225], v[12:15]
	v_mfma_f32_16x16x32_bf16 v[8:11], v[190:193], v[222:225], v[8:11]
	s_barrier
; #define PG8_STAGE(bufoff, gbase, v0, v1) do { \
;         __builtin_amdgcn_global_load_lds((const unsigned*)((const char*)(gbase) + (v0)), (LAS unsigned*)(lds + (bufoff) + ldsw), 16, 0, 0); \
;         __builtin_amdgcn_global_load_lds((const unsigned*)((const char*)(gbase) + (v1)), (LAS unsigned*)(lds + (bufoff) + ldsw + 8192), 16, 0, 0); } while (0)
; #define PG8_LDA(dst, b, h) do { _Pragma("unroll") for (int m = 0; m < 4; ++m) _Pragma("unroll") for (int k = 0; k < 2; ++k) dst[m][k] = *(const LAS bf16x8*)(lds + PG8_SA(b, h) + aoff + m * 2048 + k * 1024); } while (0)
; #define PG8_LDB(dst, b, h) do { _Pragma("unroll") for (int n = 0; n < 2; ++n) _Pragma("unroll") for (int k = 0; k < 2; ++k) dst[n][k] = *(const LAS bf16x8*)(lds + PG8_SB(b, h) + boff + n * 2048 + k * 1024); } while (0)
; #define PG8_MMA(ai, bj, At, Bt) do { __builtin_amdgcn_s_setprio(1); _Pragma("unroll") for (int m = 0; m < 4; ++m) _Pragma("unroll") for (int n = 0; n < 2; ++n) _Pragma("unroll") for (int k = 0; k < 2; ++k) \
;         acc[ai][bj][m][n] = __builtin_amdgcn_mfma_f32_16x16x32_bf16(Bt[n][k], At[m][k], acc[ai][bj][m][n], 0, 0, 0); __builtin_amdgcn_s_setprio(0); } while (0)
; #define PG8_WAIT_V(n) asm volatile("s_waitcnt vmcnt(" #n ")" ::: "memory")
; #define PG8_WAIT_L(n) asm volatile("s_waitcnt lgkmcnt(" #n ")" ::: "memory")
; #define PG8_BAR __builtin_amdgcn_s_barrier()
; #define PG8_SCHED __builtin_amdgcn_sched_barrier(0)
; template <class Epi, class Sched>
; __device__ __forceinline__ void gemm_phase(LAS unsigned char* lds, const Sched& S, const Epi& E) {
;     ...
;             PG8_STAGE(PG8_SB(0, 1), b2 + xhB, xB0, xB1);
;             PG8_WAIT_V(6); PG8_BAR; PG8_MMA(1, 1, At, B1); PG8_BAR;
;             PG8_LDB(B0, 1, 0); PG8_SCHED; PG8_LDA(At, 1, 0); PG8_STAGE(PG8_SA(0, 1), a2 + xhA, xA0, xA1);
;             PG8_WAIT_L(8); PG8_BAR; PG8_WAIT_L(0); PG8_MMA(0, 0, At, B0); PG8_BAR; PG8_SCHED;
;             PG8_LDB(B1, 1, 1); PG8_STAGE(PG8_SB(1, 0), b3, xB0, xB1);
;             PG8_BAR; PG8_WAIT_L(0); PG8_MMA(0, 1, At, B1); PG8_BAR;
	s_add_u32 s70, s38, 0x80000
	s_addc_u32 s71, s39, 0
	s_add_i32 s21, s69, s43
	s_mov_b32 m0, s21
	s_nop 0
	global_load_lds_dwordx4 v136, s[70:71]
	s_add_i32 m0, s21, 0x2000
	s_nop 0
	global_load_lds_dwordx4 v146, s[70:71]
	s_waitcnt vmcnt(6)
	s_barrier
	v_mfma_f32_16x16x32_bf16 v[52:55], v[226:229], v[194:197], v[52:55]
	v_mfma_f32_16x16x32_bf16 v[48:51], v[234:237], v[194:197], v[48:51]
	v_mfma_f32_16x16x32_bf16 v[36:39], v[226:229], v[202:205], v[36:39]
	v_mfma_f32_16x16x32_bf16 v[32:35], v[234:237], v[202:205], v[32:35]
	v_mfma_f32_16x16x32_bf16 v[20:23], v[226:229], v[210:213], v[20:23]
	v_mfma_f32_16x16x32_bf16 v[16:19], v[234:237], v[210:213], v[16:19]
	v_mfma_f32_16x16x32_bf16 v[4:7], v[226:229], v[218:221], v[4:7]
	v_mfma_f32_16x16x32_bf16 v[0:3], v[234:237], v[218:221], v[0:3]
	v_mfma_f32_16x16x32_bf16 v[52:55], v[230:233], v[198:201], v[52:55]
	v_mfma_f32_16x16x32_bf16 v[48:51], v[238:241], v[198:201], v[48:51]
	v_mfma_f32_16x16x32_bf16 v[36:39], v[230:233], v[206:209], v[36:39]
	v_mfma_f32_16x16x32_bf16 v[32:35], v[238:241], v[206:209], v[32:35]
	v_mfma_f32_16x16x32_bf16 v[20:23], v[230:233], v[214:217], v[20:23]
	v_mfma_f32_16x16x32_bf16 v[16:19], v[238:241], v[214:217], v[16:19]
	v_mfma_f32_16x16x32_bf16 v[4:7], v[230:233], v[222:225], v[4:7]
	v_mfma_f32_16x16x32_bf16 v[0:3], v[238:241], v[222:225], v[0:3]
	s_add_i32 s21, 0, 0x18000
	v_add_u32_e32 v147, s21, v155
	s_barrier
	ds_read_b128 v[158:161], v147
	ds_read_b128 v[182:185], v147 offset:1024
	ds_read_b128 v[186:189], v147 offset:2048
	ds_read_b128 v[190:193], v147 offset:3072
	s_add_u32 s40, s40, 0x80000
	s_addc_u32 s41, s41, 0
	s_mov_b32 m0, s50
	v_lshl_add_u64 v[150:151], s[40:41], 0, v[150:151]
	ds_read_b128 v[194:197], v143 offset:32768
	ds_read_b128 v[198:201], v143 offset:33792
	ds_read_b128 v[202:205], v143 offset:34816
	ds_read_b128 v[206:209], v143 offset:35840
	ds_read_b128 v[210:213], v143 offset:36864
	ds_read_b128 v[214:217], v143 offset:37888
	ds_read_b128 v[218:221], v143 offset:38912
	ds_read_b128 v[222:225], v143 offset:39936
	global_load_lds_dwordx4 v[150:151], off
	v_lshl_add_u64 v[148:149], s[40:41], 0, v[148:149]
	s_mov_b32 m0, s51
	s_nop 0
	global_load_lds_dwordx4 v[148:149], off
	s_waitcnt lgkmcnt(8)
	s_barrier
	s_waitcnt lgkmcnt(0)
	v_mfma_f32_16x16x32_bf16 v[124:127], v[158:161], v[194:197], v[124:127]
	v_mfma_f32_16x16x32_bf16 v[120:123], v[186:189], v[194:197], v[120:123]
	v_mfma_f32_16x16x32_bf16 v[112:115], v[158:161], v[202:205], v[112:115]
	v_mfma_f32_16x16x32_bf16 v[104:107], v[186:189], v[202:205], v[104:107]
	v_mfma_f32_16x16x32_bf16 v[96:99], v[158:161], v[210:213], v[96:99]
	v_mfma_f32_16x16x32_bf16 v[88:91], v[186:189], v[210:213], v[88:91]
	v_mfma_f32_16x16x32_bf16 v[80:83], v[158:161], v[218:221], v[80:83]
	v_mfma_f32_16x16x32_bf16 v[72:75], v[186:189], v[218:221], v[72:75]
	v_mfma_f32_16x16x32_bf16 v[124:127], v[182:185], v[198:201], v[124:127]
	v_mfma_f32_16x16x32_bf16 v[120:123], v[190:193], v[198:201], v[120:123]
	v_mfma_f32_16x16x32_bf16 v[112:115], v[182:185], v[206:209], v[112:115]
	v_mfma_f32_16x16x32_bf16 v[104:107], v[190:193], v[206:209], v[104:107]
	v_mfma_f32_16x16x32_bf16 v[96:99], v[182:185], v[214:217], v[96:99]
	v_mfma_f32_16x16x32_bf16 v[88:91], v[190:193], v[214:217], v[88:91]
	v_mfma_f32_16x16x32_bf16 v[80:83], v[182:185], v[222:225], v[80:83]
	v_mfma_f32_16x16x32_bf16 v[72:75], v[190:193], v[222:225], v[72:75]
	s_barrier
	s_add_i32 s40, 0, 0x1c000
	s_add_i32 s21, s21, s43
	v_add_u32_e32 v147, s40, v155
	v_lshl_add_u64 v[138:139], v[138:139], 0, s[44:45]
	s_mov_b32 m0, s21
	ds_read_b128 v[148:151], v147
	ds_read_b128 v[226:229], v147 offset:1024
	ds_read_b128 v[230:233], v147 offset:2048
	ds_read_b128 v[234:237], v147 offset:3072
	global_load_lds_dwordx4 v[138:139], off
	v_lshl_add_u64 v[138:139], v[140:141], 0, s[44:45]
	s_add_i32 m0, s21, 0x2000
	s_nop 0
	global_load_lds_dwordx4 v[138:139], off
	s_barrier
; #define PG8_STAGE(bufoff, gbase, v0, v1) do { \
;         __builtin_amdgcn_global_load_lds((const unsigned*)((const char*)(gbase) + (v0)), (LAS unsigned*)(lds + (bufoff) + ldsw), 16, 0, 0); \
;         __builtin_amdgcn_global_load_lds((const unsigned*)((const char*)(gbase) + (v1)), (LAS unsigned*)(lds + (bufoff) + ldsw + 8192), 16, 0, 0); } while (0)
; #define PG8_LDA(dst, b, h) do { _Pragma("unroll") for (int m = 0; m < 4; ++m) _Pragma("unroll") for (int k = 0; k < 2; ++k) dst[m][k] = *(const LAS bf16x8*)(lds + PG8_SA(b, h) + aoff + m * 2048 + k * 1024); } while (0)
; #define PG8_MMA(ai, bj, At, Bt) do { __builtin_amdgcn_s_setprio(1); _Pragma("unroll") for (int m = 0; m < 4; ++m) _Pragma("unroll") for (int n = 0; n < 2; ++n) _Pragma("unroll") for (int k = 0; k < 2; ++k) \
;         acc[ai][bj][m][n] = __builtin_amdgcn_mfma_f32_16x16x32_bf16(Bt[n][k], At[m][k], acc[ai][bj][m][n], 0, 0, 0); __builtin_amdgcn_s_setprio(0); } while (0)
; #define PG8_WAIT_V(n) asm volatile("s_waitcnt vmcnt(" #n ")" ::: "memory")
; #define PG8_WAIT_L(n) asm volatile("s_waitcnt lgkmcnt(" #n ")" ::: "memory")
; #define PG8_BAR __builtin_amdgcn_s_barrier()
; #define PG8_SCHED __builtin_amdgcn_sched_barrier(0)
; template <class Epi, class Sched>
; __device__ __forceinline__ void gemm_phase(LAS unsigned char* lds, const Sched& S, const Epi& E) {
;     ...
;             const bool last = (t == nt - 2);
;             const char* a1 = cA + (size_t)(t + 1) * kstep;
;             const char* a2 = last ? nA : cA + (size_t)(t + 2) * kstep; const char* b2 = last ? nB : cB + (size_t)(t + 2) * kstep;
;             const char* a3 = a2 + kstep; const char* b3 = b2 + kstep;
;             const unsigned xA0 = last ? nvA0 : vA0, xA1 = last ? nvA1 : vA1, xB0 = last ? nvB0 : vB0, xB1 = last ? nvB1 : vB1;
;             const size_t xhA = last ? nhA : hA, xhB = last ? nhB : hB;
;     ...
;             PG8_BAR; PG8_WAIT_L(0); PG8_MMA(0, 1, At, B1); PG8_BAR;
;             PG8_LDA(At, 1, 1); PG8_STAGE(PG8_SA(1, 0), a3, xA0, xA1);
;             PG8_BAR; PG8_WAIT_L(0); PG8_MMA(1, 0, At, B0); PG8_BAR; PG8_SCHED;
;             PG8_STAGE(PG8_SB(1, 1), b3 + xhB, xB0, xB1);
;             PG8_WAIT_V(6); PG8_BAR; PG8_MMA(1, 1, At, B1); PG8_BAR;
;         }
	s_waitcnt lgkmcnt(0)
	v_mfma_f32_16x16x32_bf16 v[116:119], v[148:151], v[194:197], v[116:119]
	v_mfma_f32_16x16x32_bf16 v[108:111], v[230:233], v[194:197], v[108:111]
	v_mfma_f32_16x16x32_bf16 v[100:103], v[148:151], v[202:205], v[100:103]
	v_mfma_f32_16x16x32_bf16 v[92:95], v[230:233], v[202:205], v[92:95]
	v_mfma_f32_16x16x32_bf16 v[84:87], v[148:151], v[210:213], v[84:87]
	v_mfma_f32_16x16x32_bf16 v[76:79], v[230:233], v[210:213], v[76:79]
	v_mfma_f32_16x16x32_bf16 v[68:71], v[148:151], v[218:221], v[68:71]
	v_mfma_f32_16x16x32_bf16 v[64:67], v[230:233], v[218:221], v[64:67]
	v_mfma_f32_16x16x32_bf16 v[116:119], v[226:229], v[198:201], v[116:119]
	v_mfma_f32_16x16x32_bf16 v[108:111], v[234:237], v[198:201], v[108:111]
	v_mfma_f32_16x16x32_bf16 v[100:103], v[226:229], v[206:209], v[100:103]
	v_mfma_f32_16x16x32_bf16 v[92:95], v[234:237], v[206:209], v[92:95]
	v_mfma_f32_16x16x32_bf16 v[84:87], v[226:229], v[214:217], v[84:87]
	v_mfma_f32_16x16x32_bf16 v[76:79], v[234:237], v[214:217], v[76:79]
	v_mfma_f32_16x16x32_bf16 v[68:71], v[226:229], v[222:225], v[68:71]
	v_mfma_f32_16x16x32_bf16 v[64:67], v[234:237], v[222:225], v[64:67]
	s_mov_b32 m0, s64
	v_lshl_add_u64 v[138:139], v[242:243], 0, s[44:45]
	s_barrier
	ds_read_b128 v[194:197], v143 offset:49152
	ds_read_b128 v[198:201], v143 offset:50176
	ds_read_b128 v[202:205], v143 offset:51200
	ds_read_b128 v[206:209], v143 offset:52224
	ds_read_b128 v[210:213], v143 offset:53248
	ds_read_b128 v[214:217], v143 offset:54272
	ds_read_b128 v[218:221], v143 offset:55296
	ds_read_b128 v[222:225], v143 offset:56320
	global_load_lds_dwordx4 v[138:139], off
	v_lshl_add_u64 v[138:139], v[244:245], 0, s[44:45]
	s_mov_b32 m0, s65
	s_nop 0
	global_load_lds_dwordx4 v[138:139], off
	s_barrier
	s_waitcnt lgkmcnt(0)
	v_mfma_f32_16x16x32_bf16 v[60:63], v[158:161], v[194:197], v[60:63]
	v_mfma_f32_16x16x32_bf16 v[56:59], v[186:189], v[194:197], v[56:59]
	v_mfma_f32_16x16x32_bf16 v[44:47], v[158:161], v[202:205], v[44:47]
	v_mfma_f32_16x16x32_bf16 v[40:43], v[186:189], v[202:205], v[40:43]
	v_mfma_f32_16x16x32_bf16 v[28:31], v[158:161], v[210:213], v[28:31]
	v_mfma_f32_16x16x32_bf16 v[24:27], v[186:189], v[210:213], v[24:27]
	v_mfma_f32_16x16x32_bf16 v[12:15], v[158:161], v[218:221], v[12:15]
	v_mfma_f32_16x16x32_bf16 v[8:11], v[186:189], v[218:221], v[8:11]
	v_mfma_f32_16x16x32_bf16 v[60:63], v[182:185], v[198:201], v[60:63]
	v_mfma_f32_16x16x32_bf16 v[56:59], v[190:193], v[198:201], v[56:59]
	v_mfma_f32_16x16x32_bf16 v[44:47], v[182:185], v[206:209], v[44:47]
	v_mfma_f32_16x16x32_bf16 v[40:43], v[190:193], v[206:209], v[40:43]
	v_mfma_f32_16x16x32_bf16 v[28:31], v[182:185], v[214:217], v[28:31]
	v_mfma_f32_16x16x32_bf16 v[24:27], v[190:193], v[214:217], v[24:27]
	v_mfma_f32_16x16x32_bf16 v[12:15], v[182:185], v[222:225], v[12:15]
	v_mfma_f32_16x16x32_bf16 v[8:11], v[190:193], v[222:225], v[8:11]
	s_barrier
	s_add_u32 s38, s38, 0x80080
	s_addc_u32 s39, s39, 0
	s_add_i32 s21, s40, s43
	s_mov_b32 m0, s21
	s_nop 0
	global_load_lds_dwordx4 v136, s[38:39]
	s_add_i32 m0, s21, 0x2000
	s_nop 0
	global_load_lds_dwordx4 v146, s[38:39]
	s_waitcnt vmcnt(6)
	s_barrier
	v_mfma_f32_16x16x32_bf16 v[52:55], v[148:151], v[194:197], v[52:55]
	v_mfma_f32_16x16x32_bf16 v[48:51], v[230:233], v[194:197], v[48:51]
	v_mfma_f32_16x16x32_bf16 v[36:39], v[148:151], v[202:205], v[36:39]
	v_mfma_f32_16x16x32_bf16 v[32:35], v[230:233], v[202:205], v[32:35]
	v_mfma_f32_16x16x32_bf16 v[20:23], v[148:151], v[210:213], v[20:23]
	v_mfma_f32_16x16x32_bf16 v[16:19], v[230:233], v[210:213], v[16:19]
	v_mfma_f32_16x16x32_bf16 v[4:7], v[148:151], v[218:221], v[4:7]
	v_mfma_f32_16x16x32_bf16 v[0:3], v[230:233], v[218:221], v[0:3]
	v_mfma_f32_16x16x32_bf16 v[52:55], v[226:229], v[198:201], v[52:55]
	v_mfma_f32_16x16x32_bf16 v[48:51], v[234:237], v[198:201], v[48:51]
	v_mfma_f32_16x16x32_bf16 v[36:39], v[226:229], v[206:209], v[36:39]
	v_mfma_f32_16x16x32_bf16 v[32:35], v[234:237], v[206:209], v[32:35]
	v_mfma_f32_16x16x32_bf16 v[20:23], v[226:229], v[214:217], v[20:23]
	v_mfma_f32_16x16x32_bf16 v[16:19], v[234:237], v[214:217], v[16:19]
	v_mfma_f32_16x16x32_bf16 v[4:7], v[226:229], v[222:225], v[4:7]
	v_mfma_f32_16x16x32_bf16 v[0:3], v[234:237], v[222:225], v[0:3]
	s_add_i32 s15, s15, 2
	s_add_u32 s26, s26, 0x100
	s_addc_u32 s27, s27, 0
	s_add_u32 s34, s34, 0x100
	s_addc_u32 s35, s35, 0
	s_cmp_gt_u32 s15, 29
	s_cbranch_scc1 .Lrot_exit_3
	s_cmp_eq_u32 s15, 28
	s_cselect_b64 s[40:41], -1, 0
	s_and_b64 vcc, exec, s[40:41]
	v_mov_b64_e32 v[148:149], v[130:131]
	v_mov_b64_e32 v[150:151], v[128:129]
	v_mov_b32_e32 v146, v156
	v_mov_b32_e32 v136, v145
	s_mov_b64 s[38:39], s[24:25]
	s_cbranch_vccnz .Lrot_join_3
	v_mov_b64_e32 v[148:149], v[134:135]
	v_mov_b64_e32 v[150:151], v[132:133]
	v_mov_b32_e32 v146, v142
	v_mov_b32_e32 v136, v144
	s_mov_b64 s[38:39], s[34:35]

; #define PG8_STAGE(bufoff, gbase, v0, v1) do { \
;         __builtin_amdgcn_global_load_lds((const unsigned*)((const char*)(gbase) + (v0)), (LAS unsigned*)(lds + (bufoff) + ldsw), 16, 0, 0); \
;         __builtin_amdgcn_global_load_lds((const unsigned*)((const char*)(gbase) + (v1)), (LAS unsigned*)(lds + (bufoff) + ldsw + 8192), 16, 0, 0); } while (0)
; #define PG8_LDA(dst, b, h) do { _Pragma("unroll") for (int m = 0; m < 4; ++m) _Pragma("unroll") for (int k = 0; k < 2; ++k) dst[m][k] = *(const LAS bf16x8*)(lds + PG8_SA(b, h) + aoff + m * 2048 + k * 1024); } while (0)
; #define PG8_LDB(dst, b, h) do { _Pragma("unroll") for (int n = 0; n < 2; ++n) _Pragma("unroll") for (int k = 0; k < 2; ++k) dst[n][k] = *(const LAS bf16x8*)(lds + PG8_SB(b, h) + boff + n * 2048 + k * 1024); } while (0)
; #define PG8_MMA(ai, bj, At, Bt) do { __builtin_amdgcn_s_setprio(1); _Pragma("unroll") for (int m = 0; m < 4; ++m) _Pragma("unroll") for (int n = 0; n < 2; ++n) _Pragma("unroll") for (int k = 0; k < 2; ++k) \
;         acc[ai][bj][m][n] = __builtin_amdgcn_mfma_f32_16x16x32_bf16(Bt[n][k], At[m][k], acc[ai][bj][m][n], 0, 0, 0); __builtin_amdgcn_s_setprio(0); } while (0)
; template <class Epi, class Sched>
; __device__ __forceinline__ void gemm_phase(LAS unsigned char* lds, const Sched& S, const Epi& E) {
;     ...
;         for (int t = 0; t < nt; t += 2) {
;             const bool last = (t == nt - 2);
;             const char* a1 = cA + (size_t)(t + 1) * kstep;
;             const char* a2 = last ? nA : cA + (size_t)(t + 2) * kstep; const char* b2 = last ? nB : cB + (size_t)(t + 2) * kstep;
;             const char* a3 = a2 + kstep; const char* b3 = b2 + kstep;
;             const unsigned xA0 = last ? nvA0 : vA0, xA1 = last ? nvA1 : vA1, xB0 = last ? nvB0 : vB0, xB1 = last ? nvB1 : vB1;
;             const size_t xhA = last ? nhA : hA, xhB = last ? nhB : hB;
;             PG8_LDB(B0, 0, 0); PG8_SCHED; PG8_LDA(At, 0, 0); PG8_STAGE(PG8_SA(1, 1), a1 + hA, vA0, vA1);
;             PG8_WAIT_L(8); PG8_BAR; PG8_WAIT_L(0); PG8_MMA(0, 0, At, B0); PG8_BAR; PG8_SCHED;
;             PG8_LDB(B1, 0, 1); PG8_STAGE(PG8_SB(0, 0), b2, xB0, xB1);
;             PG8_BAR; PG8_WAIT_L(0); PG8_MMA(0, 1, At, B1); PG8_BAR;
;             PG8_LDA(At, 0, 1); PG8_STAGE(PG8_SA(0, 0), a2, xA0, xA1);
;             PG8_BAR; PG8_WAIT_L(0); PG8_MMA(1, 0, At, B0); PG8_BAR; PG8_SCHED;
.LBB0_847:
	s_add_u32 s15, s24, 0xffe00080
	s_addc_u32 s70, s25, -1
	s_and_b64 s[38:39], exec, s[38:39]
	s_cselect_b32 s39, s21, s70
	s_cselect_b32 s38, s20, s15
	s_add_i32 s15, 0, 0x10000
	v_add_u32_e32 v138, s15, v147
	ds_read_b128 v[150:153], v138
	ds_read_b128 v[154:157], v138 offset:1024
	ds_read_b128 v[158:161], v138 offset:2048
	ds_read_b128 v[182:185], v138 offset:3072
	v_lshl_add_u64 v[138:139], s[24:25], 0, v[136:137]
	s_add_i32 m0, s49, 0xc000
	ds_read_b128 v[186:189], v148
	ds_read_b128 v[190:193], v148 offset:1024
	ds_read_b128 v[194:197], v148 offset:2048
	ds_read_b128 v[198:201], v148 offset:3072
	ds_read_b128 v[202:205], v148 offset:4096
	ds_read_b128 v[206:209], v148 offset:5120
	ds_read_b128 v[210:213], v148 offset:6144
	ds_read_b128 v[214:217], v148 offset:7168
	global_load_lds_dwordx4 v[138:139], off
	v_lshl_add_u64 v[138:139], s[24:25], 0, v[132:133]
	s_add_i32 m0, s49, 0xe000
	s_nop 0
	global_load_lds_dwordx4 v[138:139], off
	s_waitcnt lgkmcnt(8)
	s_barrier
	s_waitcnt lgkmcnt(0)
	v_mfma_f32_16x16x32_bf16 v[124:127], v[150:153], v[186:189], v[124:127]
	v_mfma_f32_16x16x32_bf16 v[120:123], v[158:161], v[186:189], v[120:123]
	v_mfma_f32_16x16x32_bf16 v[108:111], v[150:153], v[194:197], v[108:111]
	v_mfma_f32_16x16x32_bf16 v[104:107], v[158:161], v[194:197], v[104:107]
	v_mfma_f32_16x16x32_bf16 v[100:103], v[150:153], v[202:205], v[100:103]
	v_mfma_f32_16x16x32_bf16 v[96:99], v[158:161], v[202:205], v[96:99]
	v_mfma_f32_16x16x32_bf16 v[84:87], v[150:153], v[210:213], v[84:87]
	v_mfma_f32_16x16x32_bf16 v[80:83], v[158:161], v[210:213], v[80:83]
	v_mfma_f32_16x16x32_bf16 v[124:127], v[154:157], v[190:193], v[124:127]
	v_mfma_f32_16x16x32_bf16 v[120:123], v[182:185], v[190:193], v[120:123]
	v_mfma_f32_16x16x32_bf16 v[108:111], v[154:157], v[198:201], v[108:111]
	v_mfma_f32_16x16x32_bf16 v[104:107], v[182:185], v[198:201], v[104:107]
	v_mfma_f32_16x16x32_bf16 v[100:103], v[154:157], v[206:209], v[100:103]
	v_mfma_f32_16x16x32_bf16 v[96:99], v[182:185], v[206:209], v[96:99]
	v_mfma_f32_16x16x32_bf16 v[84:87], v[154:157], v[214:217], v[84:87]
	v_mfma_f32_16x16x32_bf16 v[80:83], v[182:185], v[214:217], v[80:83]
	s_barrier
	s_add_i32 s82, 0, 0x14000
	v_add_u32_e32 v138, s82, v147
	s_add_i32 s15, s15, s48
	ds_read_b128 v[218:221], v138
	ds_read_b128 v[222:225], v138 offset:1024
	ds_read_b128 v[226:229], v138 offset:2048
	ds_read_b128 v[230:233], v138 offset:3072
	v_lshl_add_u64 v[138:139], s[34:35], 0, v[142:143]
	s_mov_b32 m0, s15
	v_lshl_add_u64 v[140:141], s[34:35], 0, v[134:135]
	global_load_lds_dwordx4 v[138:139], off
	s_add_i32 m0, s15, 0x2000
	s_nop 0
	global_load_lds_dwordx4 v[140:141], off
	s_barrier
	s_waitcnt lgkmcnt(0)
	v_mfma_f32_16x16x32_bf16 v[116:119], v[218:221], v[186:189], v[116:119]
	v_mfma_f32_16x16x32_bf16 v[112:115], v[226:229], v[186:189], v[112:115]
	v_mfma_f32_16x16x32_bf16 v[92:95], v[218:221], v[194:197], v[92:95]
	v_mfma_f32_16x16x32_bf16 v[88:91], v[226:229], v[194:197], v[88:91]
	v_mfma_f32_16x16x32_bf16 v[76:79], v[218:221], v[202:205], v[76:79]
	v_mfma_f32_16x16x32_bf16 v[72:75], v[226:229], v[202:205], v[72:75]
	v_mfma_f32_16x16x32_bf16 v[68:71], v[218:221], v[210:213], v[68:71]
	v_mfma_f32_16x16x32_bf16 v[64:67], v[226:229], v[210:213], v[64:67]
	v_mfma_f32_16x16x32_bf16 v[116:119], v[222:225], v[190:193], v[116:119]
	v_mfma_f32_16x16x32_bf16 v[112:115], v[230:233], v[190:193], v[112:115]
	v_mfma_f32_16x16x32_bf16 v[92:95], v[222:225], v[198:201], v[92:95]
	v_mfma_f32_16x16x32_bf16 v[88:91], v[230:233], v[198:201], v[88:91]
	v_mfma_f32_16x16x32_bf16 v[76:79], v[222:225], v[206:209], v[76:79]
	v_mfma_f32_16x16x32_bf16 v[72:75], v[230:233], v[206:209], v[72:75]
	v_mfma_f32_16x16x32_bf16 v[68:71], v[222:225], v[214:217], v[68:71]
	v_mfma_f32_16x16x32_bf16 v[64:67], v[230:233], v[214:217], v[64:67]
	s_mov_b32 m0, s49
	v_lshl_add_u64 v[234:235], s[38:39], 0, v[142:143]
	s_barrier
	ds_read_b128 v[186:189], v148 offset:16384
	ds_read_b128 v[190:193], v148 offset:17408
	ds_read_b128 v[194:197], v148 offset:18432
	ds_read_b128 v[198:201], v148 offset:19456
	ds_read_b128 v[202:205], v148 offset:20480
	ds_read_b128 v[206:209], v148 offset:21504
	ds_read_b128 v[210:213], v148 offset:22528
	ds_read_b128 v[214:217], v148 offset:23552
	global_load_lds_dwordx4 v[234:235], off
	v_lshl_add_u64 v[236:237], s[38:39], 0, v[134:135]
	s_mov_b32 m0, s50
	s_nop 0
	global_load_lds_dwordx4 v[236:237], off
	s_barrier
	s_waitcnt lgkmcnt(0)
	v_mfma_f32_16x16x32_bf16 v[60:63], v[150:153], v[186:189], v[60:63]
	v_mfma_f32_16x16x32_bf16 v[56:59], v[158:161], v[186:189], v[56:59]
	v_mfma_f32_16x16x32_bf16 v[44:47], v[150:153], v[194:197], v[44:47]
	v_mfma_f32_16x16x32_bf16 v[40:43], v[158:161], v[194:197], v[40:43]
	v_mfma_f32_16x16x32_bf16 v[28:31], v[150:153], v[202:205], v[28:31]
	v_mfma_f32_16x16x32_bf16 v[24:27], v[158:161], v[202:205], v[24:27]
	v_mfma_f32_16x16x32_bf16 v[12:15], v[150:153], v[210:213], v[12:15]
	v_mfma_f32_16x16x32_bf16 v[8:11], v[158:161], v[210:213], v[8:11]
	v_mfma_f32_16x16x32_bf16 v[60:63], v[154:157], v[190:193], v[60:63]
	v_mfma_f32_16x16x32_bf16 v[56:59], v[182:185], v[190:193], v[56:59]
	v_mfma_f32_16x16x32_bf16 v[44:47], v[154:157], v[198:201], v[44:47]
	v_mfma_f32_16x16x32_bf16 v[40:43], v[182:185], v[198:201], v[40:43]
	v_mfma_f32_16x16x32_bf16 v[28:31], v[154:157], v[206:209], v[28:31]
	v_mfma_f32_16x16x32_bf16 v[24:27], v[182:185], v[206:209], v[24:27]
	v_mfma_f32_16x16x32_bf16 v[12:15], v[154:157], v[214:217], v[12:15]
	v_mfma_f32_16x16x32_bf16 v[8:11], v[182:185], v[214:217], v[8:11]
	s_barrier
; #define PG8_STAGE(bufoff, gbase, v0, v1) do { \
;         __builtin_amdgcn_global_load_lds((const unsigned*)((const char*)(gbase) + (v0)), (LAS unsigned*)(lds + (bufoff) + ldsw), 16, 0, 0); \
;         __builtin_amdgcn_global_load_lds((const unsigned*)((const char*)(gbase) + (v1)), (LAS unsigned*)(lds + (bufoff) + ldsw + 8192), 16, 0, 0); } while (0)
; #define PG8_LDA(dst, b, h) do { _Pragma("unroll") for (int m = 0; m < 4; ++m) _Pragma("unroll") for (int k = 0; k < 2; ++k) dst[m][k] = *(const LAS bf16x8*)(lds + PG8_SA(b, h) + aoff + m * 2048 + k * 1024); } while (0)
; #define PG8_LDB(dst, b, h) do { _Pragma("unroll") for (int n = 0; n < 2; ++n) _Pragma("unroll") for (int k = 0; k < 2; ++k) dst[n][k] = *(const LAS bf16x8*)(lds + PG8_SB(b, h) + boff + n * 2048 + k * 1024); } while (0)
; #define PG8_MMA(ai, bj, At, Bt) do { __builtin_amdgcn_s_setprio(1); _Pragma("unroll") for (int m = 0; m < 4; ++m) _Pragma("unroll") for (int n = 0; n < 2; ++n) _Pragma("unroll") for (int k = 0; k < 2; ++k) \
;         acc[ai][bj][m][n] = __builtin_amdgcn_mfma_f32_16x16x32_bf16(Bt[n][k], At[m][k], acc[ai][bj][m][n], 0, 0, 0); __builtin_amdgcn_s_setprio(0); } while (0)
; #define PG8_WAIT_V(n) asm volatile("s_waitcnt vmcnt(" #n ")" ::: "memory")
; #define PG8_WAIT_L(n) asm volatile("s_waitcnt lgkmcnt(" #n ")" ::: "memory")
; #define PG8_BAR __builtin_amdgcn_s_barrier()
; #define PG8_SCHED __builtin_amdgcn_sched_barrier(0)
; template <class Epi, class Sched>
; __device__ __forceinline__ void gemm_phase(LAS unsigned char* lds, const Sched& S, const Epi& E) {
;     ...
;             PG8_STAGE(PG8_SB(0, 1), b2 + xhB, xB0, xB1);
;             PG8_WAIT_V(6); PG8_BAR; PG8_MMA(1, 1, At, B1); PG8_BAR;
;             PG8_LDB(B0, 1, 0); PG8_SCHED; PG8_LDA(At, 1, 0); PG8_STAGE(PG8_SA(0, 1), a2 + xhA, xA0, xA1);
;             PG8_WAIT_L(8); PG8_BAR; PG8_WAIT_L(0); PG8_MMA(0, 0, At, B0); PG8_BAR; PG8_SCHED;
;             PG8_LDB(B1, 1, 1); PG8_STAGE(PG8_SB(1, 0), b3, xB0, xB1);
	s_add_u32 s70, s34, 0x200000
	s_addc_u32 s71, s35, 0
	s_add_i32 s15, s82, s48
	v_lshl_add_u64 v[150:151], s[70:71], 0, v[142:143]
	s_mov_b32 m0, s15
	s_nop 0
	global_load_lds_dwordx4 v[150:151], off
	v_lshl_add_u64 v[150:151], s[70:71], 0, v[134:135]
	s_add_i32 m0, s15, 0x2000
	s_nop 0
	global_load_lds_dwordx4 v[150:151], off
	s_waitcnt vmcnt(6)
	s_barrier
	v_mfma_f32_16x16x32_bf16 v[52:55], v[218:221], v[186:189], v[52:55]
	v_mfma_f32_16x16x32_bf16 v[48:51], v[226:229], v[186:189], v[48:51]
	v_mfma_f32_16x16x32_bf16 v[36:39], v[218:221], v[194:197], v[36:39]
	v_mfma_f32_16x16x32_bf16 v[32:35], v[226:229], v[194:197], v[32:35]
	v_mfma_f32_16x16x32_bf16 v[20:23], v[218:221], v[202:205], v[20:23]
	v_mfma_f32_16x16x32_bf16 v[16:19], v[226:229], v[202:205], v[16:19]
	v_mfma_f32_16x16x32_bf16 v[4:7], v[218:221], v[210:213], v[4:7]
	v_mfma_f32_16x16x32_bf16 v[0:3], v[226:229], v[210:213], v[0:3]
	v_mfma_f32_16x16x32_bf16 v[52:55], v[222:225], v[190:193], v[52:55]
	v_mfma_f32_16x16x32_bf16 v[48:51], v[230:233], v[190:193], v[48:51]
	v_mfma_f32_16x16x32_bf16 v[36:39], v[222:225], v[198:201], v[36:39]
	v_mfma_f32_16x16x32_bf16 v[32:35], v[230:233], v[198:201], v[32:35]
	v_mfma_f32_16x16x32_bf16 v[20:23], v[222:225], v[206:209], v[20:23]
	v_mfma_f32_16x16x32_bf16 v[16:19], v[230:233], v[206:209], v[16:19]
	v_mfma_f32_16x16x32_bf16 v[4:7], v[222:225], v[214:217], v[4:7]
	v_mfma_f32_16x16x32_bf16 v[0:3], v[230:233], v[214:217], v[0:3]
	s_add_i32 s15, 0, 0x18000
	v_add_u32_e32 v149, s15, v147
	s_barrier
	ds_read_b128 v[150:153], v149
	ds_read_b128 v[154:157], v149 offset:1024
	ds_read_b128 v[158:161], v149 offset:2048
	ds_read_b128 v[182:185], v149 offset:3072
	s_add_u32 s38, s38, 0x200000
	s_addc_u32 s39, s39, 0
	s_mov_b32 m0, s51
	v_lshl_add_u64 v[218:219], s[38:39], 0, v[142:143]
	ds_read_b128 v[186:189], v148 offset:32768
	ds_read_b128 v[190:193], v148 offset:33792
	ds_read_b128 v[194:197], v148 offset:34816
	ds_read_b128 v[198:201], v148 offset:35840
	ds_read_b128 v[202:205], v148 offset:36864
	ds_read_b128 v[206:209], v148 offset:37888
	ds_read_b128 v[210:213], v148 offset:38912
	ds_read_b128 v[214:217], v148 offset:39936
	global_load_lds_dwordx4 v[218:219], off
	v_lshl_add_u64 v[218:219], s[38:39], 0, v[134:135]
	s_mov_b32 m0, s54
	s_nop 0
	global_load_lds_dwordx4 v[218:219], off
	s_waitcnt lgkmcnt(8)
	s_barrier
	s_waitcnt lgkmcnt(0)
	v_mfma_f32_16x16x32_bf16 v[124:127], v[150:153], v[186:189], v[124:127]
	v_mfma_f32_16x16x32_bf16 v[120:123], v[158:161], v[186:189], v[120:123]
	v_mfma_f32_16x16x32_bf16 v[108:111], v[150:153], v[194:197], v[108:111]
	v_mfma_f32_16x16x32_bf16 v[104:107], v[158:161], v[194:197], v[104:107]
	v_mfma_f32_16x16x32_bf16 v[100:103], v[150:153], v[202:205], v[100:103]
	v_mfma_f32_16x16x32_bf16 v[96:99], v[158:161], v[202:205], v[96:99]
	v_mfma_f32_16x16x32_bf16 v[84:87], v[150:153], v[210:213], v[84:87]
	v_mfma_f32_16x16x32_bf16 v[80:83], v[158:161], v[210:213], v[80:83]
	v_mfma_f32_16x16x32_bf16 v[124:127], v[154:157], v[190:193], v[124:127]
	v_mfma_f32_16x16x32_bf16 v[120:123], v[182:185], v[190:193], v[120:123]
	v_mfma_f32_16x16x32_bf16 v[108:111], v[154:157], v[198:201], v[108:111]
	v_mfma_f32_16x16x32_bf16 v[104:107], v[182:185], v[198:201], v[104:107]
	v_mfma_f32_16x16x32_bf16 v[100:103], v[154:157], v[206:209], v[100:103]
	v_mfma_f32_16x16x32_bf16 v[96:99], v[182:185], v[206:209], v[96:99]
	v_mfma_f32_16x16x32_bf16 v[84:87], v[154:157], v[214:217], v[84:87]
	v_mfma_f32_16x16x32_bf16 v[80:83], v[182:185], v[214:217], v[80:83]
	s_barrier
	s_add_i32 s38, 0, 0x1c000
	s_add_i32 s15, s15, s48
	v_add_u32_e32 v149, s38, v147
	v_lshl_add_u64 v[138:139], v[138:139], 0, s[44:45]
	s_mov_b32 m0, s15
	ds_read_b128 v[218:221], v149
	ds_read_b128 v[222:225], v149 offset:1024
	ds_read_b128 v[226:229], v149 offset:2048
	ds_read_b128 v[230:233], v149 offset:3072
	global_load_lds_dwordx4 v[138:139], off
	v_lshl_add_u64 v[138:139], v[140:141], 0, s[44:45]
	s_add_i32 m0, s15, 0x2000
	s_nop 0
	global_load_lds_dwordx4 v[138:139], off
	s_barrier
; #define PG8_STAGE(bufoff, gbase, v0, v1) do { \
;         __builtin_amdgcn_global_load_lds((const unsigned*)((const char*)(gbase) + (v0)), (LAS unsigned*)(lds + (bufoff) + ldsw), 16, 0, 0); \
;         __builtin_amdgcn_global_load_lds((const unsigned*)((const char*)(gbase) + (v1)), (LAS unsigned*)(lds + (bufoff) + ldsw + 8192), 16, 0, 0); } while (0)
; #define PG8_LDA(dst, b, h) do { _Pragma("unroll") for (int m = 0; m < 4; ++m) _Pragma("unroll") for (int k = 0; k < 2; ++k) dst[m][k] = *(const LAS bf16x8*)(lds + PG8_SA(b, h) + aoff + m * 2048 + k * 1024); } while (0)
; #define PG8_LDB(dst, b, h) do { _Pragma("unroll") for (int n = 0; n < 2; ++n) _Pragma("unroll") for (int k = 0; k < 2; ++k) dst[n][k] = *(const LAS bf16x8*)(lds + PG8_SB(b, h) + boff + n * 2048 + k * 1024); } while (0)
; #define PG8_MMA(ai, bj, At, Bt) do { __builtin_amdgcn_s_setprio(1); _Pragma("unroll") for (int m = 0; m < 4; ++m) _Pragma("unroll") for (int n = 0; n < 2; ++n) _Pragma("unroll") for (int k = 0; k < 2; ++k) \
;         acc[ai][bj][m][n] = __builtin_amdgcn_mfma_f32_16x16x32_bf16(Bt[n][k], At[m][k], acc[ai][bj][m][n], 0, 0, 0); __builtin_amdgcn_s_setprio(0); } while (0)
; #define PG8_WAIT_V(n) asm volatile("s_waitcnt vmcnt(" #n ")" ::: "memory")
; template <class Epi, class Sched>
; __device__ __forceinline__ void gemm_phase(LAS unsigned char* lds, const Sched& S, const Epi& E) {
;     ...
;         for (int t = 0; t < nt; t += 2) {
;             const bool last = (t == nt - 2);
;             const char* a1 = cA + (size_t)(t + 1) * kstep;
;             const char* a2 = last ? nA : cA + (size_t)(t + 2) * kstep; const char* b2 = last ? nB : cB + (size_t)(t + 2) * kstep;
;             const char* a3 = a2 + kstep; const char* b3 = b2 + kstep;
;             const unsigned xA0 = last ? nvA0 : vA0, xA1 = last ? nvA1 : vA1, xB0 = last ? nvB0 : vB0, xB1 = last ? nvB1 : vB1;
;             const size_t xhA = last ? nhA : hA, xhB = last ? nhB : hB;
;     ...
;             PG8_LDB(B1, 1, 1); PG8_STAGE(PG8_SB(1, 0), b3, xB0, xB1);
;             PG8_BAR; PG8_WAIT_L(0); PG8_MMA(0, 1, At, B1); PG8_BAR;
;             PG8_LDA(At, 1, 1); PG8_STAGE(PG8_SA(1, 0), a3, xA0, xA1);
;             PG8_BAR; PG8_WAIT_L(0); PG8_MMA(1, 0, At, B0); PG8_BAR; PG8_SCHED;
;             PG8_STAGE(PG8_SB(1, 1), b3 + xhB, xB0, xB1);
;             PG8_WAIT_V(6); PG8_BAR; PG8_MMA(1, 1, At, B1); PG8_BAR;
;         }
	s_waitcnt lgkmcnt(0)
	v_mfma_f32_16x16x32_bf16 v[116:119], v[218:221], v[186:189], v[116:119]
	v_mfma_f32_16x16x32_bf16 v[112:115], v[226:229], v[186:189], v[112:115]
	v_mfma_f32_16x16x32_bf16 v[92:95], v[218:221], v[194:197], v[92:95]
	v_mfma_f32_16x16x32_bf16 v[88:91], v[226:229], v[194:197], v[88:91]
	v_mfma_f32_16x16x32_bf16 v[76:79], v[218:221], v[202:205], v[76:79]
	v_mfma_f32_16x16x32_bf16 v[72:75], v[226:229], v[202:205], v[72:75]
	v_mfma_f32_16x16x32_bf16 v[68:71], v[218:221], v[210:213], v[68:71]
	v_mfma_f32_16x16x32_bf16 v[64:67], v[226:229], v[210:213], v[64:67]
	v_mfma_f32_16x16x32_bf16 v[116:119], v[222:225], v[190:193], v[116:119]
	v_mfma_f32_16x16x32_bf16 v[112:115], v[230:233], v[190:193], v[112:115]
	v_mfma_f32_16x16x32_bf16 v[92:95], v[222:225], v[198:201], v[92:95]
	v_mfma_f32_16x16x32_bf16 v[88:91], v[230:233], v[198:201], v[88:91]
	v_mfma_f32_16x16x32_bf16 v[76:79], v[222:225], v[206:209], v[76:79]
	v_mfma_f32_16x16x32_bf16 v[72:75], v[230:233], v[206:209], v[72:75]
	v_mfma_f32_16x16x32_bf16 v[68:71], v[222:225], v[214:217], v[68:71]
	v_mfma_f32_16x16x32_bf16 v[64:67], v[230:233], v[214:217], v[64:67]
	s_mov_b32 m0, s65
	v_lshl_add_u64 v[138:139], v[234:235], 0, s[44:45]
	s_barrier
	ds_read_b128 v[186:189], v148 offset:49152
	ds_read_b128 v[190:193], v148 offset:50176
	ds_read_b128 v[194:197], v148 offset:51200
	ds_read_b128 v[198:201], v148 offset:52224
	ds_read_b128 v[202:205], v148 offset:53248
	ds_read_b128 v[206:209], v148 offset:54272
	ds_read_b128 v[210:213], v148 offset:55296
	ds_read_b128 v[214:217], v148 offset:56320
	global_load_lds_dwordx4 v[138:139], off
	v_lshl_add_u64 v[138:139], v[236:237], 0, s[44:45]
	s_mov_b32 m0, s66
	s_nop 0
	global_load_lds_dwordx4 v[138:139], off
	s_barrier
	s_waitcnt lgkmcnt(0)
	v_mfma_f32_16x16x32_bf16 v[60:63], v[150:153], v[186:189], v[60:63]
	v_mfma_f32_16x16x32_bf16 v[56:59], v[158:161], v[186:189], v[56:59]
	v_mfma_f32_16x16x32_bf16 v[44:47], v[150:153], v[194:197], v[44:47]
	v_mfma_f32_16x16x32_bf16 v[40:43], v[158:161], v[194:197], v[40:43]
	v_mfma_f32_16x16x32_bf16 v[28:31], v[150:153], v[202:205], v[28:31]
	v_mfma_f32_16x16x32_bf16 v[24:27], v[158:161], v[202:205], v[24:27]
	v_mfma_f32_16x16x32_bf16 v[12:15], v[150:153], v[210:213], v[12:15]
	v_mfma_f32_16x16x32_bf16 v[8:11], v[158:161], v[210:213], v[8:11]
	v_mfma_f32_16x16x32_bf16 v[60:63], v[154:157], v[190:193], v[60:63]
	v_mfma_f32_16x16x32_bf16 v[56:59], v[182:185], v[190:193], v[56:59]
	v_mfma_f32_16x16x32_bf16 v[44:47], v[154:157], v[198:201], v[44:47]
	v_mfma_f32_16x16x32_bf16 v[40:43], v[182:185], v[198:201], v[40:43]
	v_mfma_f32_16x16x32_bf16 v[28:31], v[154:157], v[206:209], v[28:31]
	v_mfma_f32_16x16x32_bf16 v[24:27], v[182:185], v[206:209], v[24:27]
	v_mfma_f32_16x16x32_bf16 v[12:15], v[154:157], v[214:217], v[12:15]
	v_mfma_f32_16x16x32_bf16 v[8:11], v[182:185], v[214:217], v[8:11]
	s_barrier
	s_add_u32 s34, s34, 0x200080
	s_addc_u32 s35, s35, 0
	s_add_i32 s15, s38, s48
	v_lshl_add_u64 v[138:139], s[34:35], 0, v[142:143]
	s_mov_b32 m0, s15
	v_lshl_add_u64 v[134:135], s[34:35], 0, v[134:135]
	global_load_lds_dwordx4 v[138:139], off
	s_add_i32 m0, s15, 0x2000
	s_nop 0
	global_load_lds_dwordx4 v[134:135], off
	s_waitcnt vmcnt(6)
	s_barrier
	v_mfma_f32_16x16x32_bf16 v[52:55], v[218:221], v[186:189], v[52:55]
	v_mfma_f32_16x16x32_bf16 v[48:51], v[226:229], v[186:189], v[48:51]
	v_mfma_f32_16x16x32_bf16 v[36:39], v[218:221], v[194:197], v[36:39]
	v_mfma_f32_16x16x32_bf16 v[32:35], v[226:229], v[194:197], v[32:35]
	v_mfma_f32_16x16x32_bf16 v[20:23], v[218:221], v[202:205], v[20:23]
	v_mfma_f32_16x16x32_bf16 v[16:19], v[226:229], v[202:205], v[16:19]
	v_mfma_f32_16x16x32_bf16 v[4:7], v[218:221], v[210:213], v[4:7]
	v_mfma_f32_16x16x32_bf16 v[0:3], v[226:229], v[210:213], v[0:3]
	v_mfma_f32_16x16x32_bf16 v[52:55], v[222:225], v[190:193], v[52:55]
	v_mfma_f32_16x16x32_bf16 v[48:51], v[230:233], v[190:193], v[48:51]
	v_mfma_f32_16x16x32_bf16 v[36:39], v[222:225], v[198:201], v[36:39]
	v_mfma_f32_16x16x32_bf16 v[32:35], v[230:233], v[198:201], v[32:35]
	v_mfma_f32_16x16x32_bf16 v[20:23], v[222:225], v[206:209], v[20:23]
	v_mfma_f32_16x16x32_bf16 v[16:19], v[230:233], v[206:209], v[16:19]
	v_mfma_f32_16x16x32_bf16 v[4:7], v[222:225], v[214:217], v[4:7]
	v_mfma_f32_16x16x32_bf16 v[0:3], v[230:233], v[214:217], v[0:3]
	s_add_i32 s11, s11, 2
	s_add_u32 s24, s24, 0x100
	s_addc_u32 s25, s25, 0
	s_add_u32 s26, s26, 0x100
	s_addc_u32 s27, s27, 0
	s_cmpk_gt_u32 s11, 0x7d
	s_cbranch_scc1 .Lrot_exit_4
	s_cmpk_eq_i32 s11, 0x7c
	s_cselect_b64 s[38:39], -1, 0
	s_and_b64 vcc, exec, s[38:39]
	v_mov_b64_e32 v[134:135], v[130:131]
	v_mov_b64_e32 v[142:143], v[128:129]
	s_mov_b64 s[34:35], s[22:23]
	s_cbranch_vccnz .Lrot_join_4
	v_mov_b64_e32 v[134:135], v[132:133]
	v_mov_b64_e32 v[142:143], v[136:137]
	s_mov_b64 s[34:35], s[26:27]
